# convert_matrix (12 copies): LDS staging pitch 260 + ds_write_b128 + half-tile bank offset, conflict-free writes and transposing reads
# speedup vs baseline: 1.0166x; 1.0062x over previous
; __device__ __forceinline__ int otid(int wv) { int t; asm volatile("v_mbcnt_lo_u32_b32 %0, -1, 0\n\tv_mbcnt_hi_u32_b32 %0, -1, %0\n\tv_lshl_add_u32 %0, %1, 6, %0" : "=&v"(t) : "s"(wv)); return t; }
; __device__ __forceinline__ int upcol(int n) { return (n >> 8) * 128 + (n & 127) + ((n & 128) ? FFD : 0); }
; __device__ void convert_matrix(int wv, const float* src, int K, int N, int ld, int perm, bf16_t* dst, float* tileL, int rot) {
;     const int tid = otid(wv), G = gridDim.x, ntk = K >> 6, ntiles = ntk * (N >> 8);
;     for (int t = (blockIdx.x + G - (rot % G)) % G; t < ntiles; t += G) {
;         const int k0 = (t % ntk) * 64, n0 = (t / ntk) * 256;
;         f32x4 v[8];
; #pragma unroll
;         for (int ps = 0; ps < 8; ++ps) { const int idx = tid + ps * NTHR, kk = idx >> 6, n4 = (idx & 63) * 4; const int sc = perm ? upcol(n0 + n4) : n0 + n4;
;             v[ps] = *(const f32x4*)(src + (size_t)(k0 + kk) * ld + sc); }
; #pragma unroll
;         for (int ps = 0; ps < 8; ++ps) { const int idx = tid + ps * NTHR, kk = idx >> 6, n4 = (idx & 63) * 4;
;             float* tp = tileL + kk * 257 + n4; tp[0] = v[ps][0]; tp[1] = v[ps][1]; tp[2] = v[ps][2]; tp[3] = v[ps][3]; }
;         __syncthreads();
.LBB0_33:
	v_cvt_f32_u32_e32 v2, s34
	s_sub_i32 s0, 0, s34
	s_add_i32 s3, s34, s2
	v_rcp_iflag_f32_e32 v2, v2
	s_nop 0
	v_mul_f32_e32 v2, 0x4f7ffffe, v2
	v_cvt_u32_f32_e32 v2, v2
	s_nop 0
	v_readfirstlane_b32 s38, v2
	s_mul_i32 s0, s0, s38
	s_mul_hi_u32 s0, s38, s0
	s_add_i32 s38, s38, s0
	s_mul_hi_u32 s0, s3, s38
	s_mul_i32 s0, s0, s34
	s_sub_i32 s0, s3, s0
	s_sub_i32 s1, s0, s34
	s_cmp_ge_u32 s0, s34
	s_cselect_b32 s0, s1, s0
	s_sub_i32 s1, s0, s34
	s_cmp_ge_u32 s0, s34
	s_cselect_b32 s0, s1, s0
	v_writelane_b32 v253, s0, 33
	s_cmpk_gt_i32 s0, 0x7f
	v_mbcnt_lo_u32_b32 v2, -1, 0
	v_mbcnt_hi_u32_b32 v2, -1, v2
	v_lshl_add_u32 v2, s33, 6, v2
	s_cbranch_scc1 .LBB0_36
	v_lshlrev_b32_e32 v3, 2, v2
	v_and_b32_e32 v4, 0xfc, v3
	v_ashrrev_i32_e32 v5, 1, v2
	v_lshlrev_b32_e32 v3, 5, v2
	v_ashrrev_i32_e32 v6, 6, v2
	v_add_u32_e32 v7, 0x200, v2
	v_add_u32_e32 v8, 0x400, v2
	v_add_u32_e32 v9, 0x600, v2
	v_add_u32_e32 v10, 0x800, v2
	v_add_u32_e32 v11, 0xa00, v2
	v_add_u32_e32 v12, 0xc00, v2
	v_add_u32_e32 v2, 0xe00, v2
	v_and_b32_e32 v22, 32, v3
	s_movk_i32 s4, 0x404
	v_ashrrev_i32_e32 v7, 6, v7
	v_ashrrev_i32_e32 v8, 6, v8
	v_ashrrev_i32_e32 v9, 6, v9
	v_ashrrev_i32_e32 v10, 6, v10
	v_ashrrev_i32_e32 v11, 6, v11
	v_ashrrev_i32_e32 v12, 6, v12
	v_ashrrev_i32_e32 v13, 6, v2
	s_add_u32 s0, s41, 0xbec600
	v_lshl_add_u32 v21, v4, 2, 0
	v_lshl_add_u32 v23, v5, 2, 0
	v_mul_u32_u24_e32 v24, 0x412, v22
	v_mul_lo_u32 v2, v6, s4
	v_mul_lo_u32 v15, v7, s4
	v_mul_lo_u32 v16, v8, s4
	v_mul_lo_u32 v17, v9, s4
	v_mul_lo_u32 v18, v10, s4
	v_mul_lo_u32 v19, v11, s4
	v_mul_lo_u32 v20, v12, s4
	v_mul_lo_u32 v25, v13, s4
	v_readlane_b32 s10, v253, 33
	v_readlane_b32 s44, v253, 17
	s_addc_u32 s1, s42, 0
	v_mov_b32_e32 v3, 0
	s_lshl_b32 s8, s10, 6
	s_lshl_b32 s9, s34, 6
	v_add_u32_e32 v14, v21, v2
	v_mad_u32_u24 v14, v6, 12, v14
	v_add_u32_e32 v15, v21, v15
	v_add_u32_e32 v16, v21, v16
	v_add_u32_e32 v17, v21, v17
	v_add_u32_e32 v18, v21, v18
	v_add_u32_e32 v19, v21, v19
	v_add_u32_e32 v20, v21, v20
	v_add_u32_e32 v21, v21, v25
	v_lshlrev_b32_e32 v2, 1, v22
	v_add_u32_e32 v22, v23, v24
	v_readlane_b32 s58, v253, 31
	v_readlane_b32 s59, v253, 32
	v_readlane_b32 s45, v253, 18
	v_readlane_b32 s46, v253, 19
	v_readlane_b32 s47, v253, 20
	v_readlane_b32 s48, v253, 21
	v_readlane_b32 s49, v253, 22
	v_readlane_b32 s50, v253, 23
	v_readlane_b32 s51, v253, 24
	v_readlane_b32 s52, v253, 25
	v_readlane_b32 s53, v253, 26
	v_readlane_b32 s54, v253, 27
	v_readlane_b32 s55, v253, 28
	v_readlane_b32 s56, v253, 29
	v_readlane_b32 s57, v253, 30
.LBB0_35:
	s_ashr_i32 s4, s10, 31
	s_lshr_b32 s4, s4, 28
	s_add_i32 s4, s10, s4
	s_ashr_i32 s4, s4, 4
	s_lshl_b32 s11, s4, 10
	s_lshl_b32 s5, s4, 8
	s_sub_i32 s4, s8, s11
	v_add_u32_e32 v26, s4, v6
	v_add_u32_e32 v28, s4, v7
	v_add_u32_e32 v30, s4, v8
	v_add_u32_e32 v32, s4, v9
	v_add_u32_e32 v34, s4, v10
	v_add_u32_e32 v36, s4, v11
	v_add_u32_e32 v38, s4, v12
	v_add_u32_e32 v40, s4, v13
	v_or_b32_e32 v24, s5, v4
	v_ashrrev_i32_e32 v27, 31, v26
	v_ashrrev_i32_e32 v29, 31, v28
	v_ashrrev_i32_e32 v31, 31, v30
	v_ashrrev_i32_e32 v33, 31, v32
	v_ashrrev_i32_e32 v35, 31, v34
	v_ashrrev_i32_e32 v37, 31, v36
	v_ashrrev_i32_e32 v39, 31, v38
	v_ashrrev_i32_e32 v41, 31, v40
	v_ashrrev_i32_e32 v25, 31, v24
	v_lshlrev_b64 v[26:27], 13, v[26:27]
	v_lshlrev_b64 v[28:29], 13, v[28:29]
	v_lshlrev_b64 v[30:31], 13, v[30:31]
	v_lshlrev_b64 v[32:33], 13, v[32:33]
	v_lshlrev_b64 v[34:35], 13, v[34:35]
	v_lshlrev_b64 v[36:37], 13, v[36:37]
	v_lshlrev_b64 v[38:39], 13, v[38:39]
	v_lshlrev_b64 v[40:41], 13, v[40:41]
	v_lshlrev_b64 v[24:25], 2, v[24:25]
	v_lshl_add_u64 v[26:27], s[58:59], 0, v[26:27]
	v_lshl_add_u64 v[28:29], s[58:59], 0, v[28:29]
	v_lshl_add_u64 v[30:31], s[58:59], 0, v[30:31]
	v_lshl_add_u64 v[32:33], s[58:59], 0, v[32:33]
	v_lshl_add_u64 v[34:35], s[58:59], 0, v[34:35]
	v_lshl_add_u64 v[36:37], s[58:59], 0, v[36:37]
	v_lshl_add_u64 v[38:39], s[58:59], 0, v[38:39]
	v_lshl_add_u64 v[40:41], s[58:59], 0, v[40:41]
	v_lshl_add_u64 v[26:27], v[26:27], 0, v[24:25]
	v_lshl_add_u64 v[28:29], v[28:29], 0, v[24:25]
	v_lshl_add_u64 v[42:43], v[30:31], 0, v[24:25]
	v_lshl_add_u64 v[44:45], v[32:33], 0, v[24:25]
	v_lshl_add_u64 v[46:47], v[34:35], 0, v[24:25]
	v_lshl_add_u64 v[48:49], v[36:37], 0, v[24:25]
	v_lshl_add_u64 v[50:51], v[38:39], 0, v[24:25]
	v_lshl_add_u64 v[52:53], v[40:41], 0, v[24:25]
	global_load_dwordx4 v[24:27], v[26:27], off
	s_nop 0
	global_load_dwordx4 v[28:31], v[28:29], off
	s_nop 0
	global_load_dwordx4 v[32:35], v[42:43], off
	global_load_dwordx4 v[36:39], v[44:45], off
	s_nop 0
	global_load_dwordx4 v[40:43], v[46:47], off
	s_nop 0
	global_load_dwordx4 v[44:47], v[48:49], off
	s_nop 0
	global_load_dwordx4 v[48:51], v[50:51], off
	s_nop 0
	global_load_dwordx4 v[52:55], v[52:53], off
	v_add_u32_e32 v56, s5, v5
	v_ashrrev_i32_e32 v57, 31, v56
	v_lshlrev_b64 v[56:57], 11, v[56:57]
	s_ashr_i32 s5, s4, 31
	v_lshl_add_u64 v[56:57], s[0:1], 0, v[56:57]
	s_add_i32 s10, s10, s34
	s_add_i32 s8, s8, s9
	v_lshl_add_u64 v[56:57], s[4:5], 1, v[56:57]
	s_cmpk_lt_i32 s10, 0x80
	v_lshl_add_u64 v[56:57], v[56:57], 0, v[2:3]
	s_waitcnt vmcnt(7)
	ds_write_b128 v14, v[24:27]
	s_waitcnt vmcnt(6)
	ds_write_b128 v14, v[28:31] offset:8320
	s_waitcnt vmcnt(5)
	ds_write_b128 v14, v[32:35] offset:16640
	s_waitcnt vmcnt(4)
	ds_write_b128 v14, v[36:39] offset:24960
	s_waitcnt vmcnt(3)
	ds_write_b128 v14, v[40:43] offset:33344
	s_waitcnt vmcnt(2)
	ds_write_b128 v14, v[44:47] offset:41664
	s_waitcnt vmcnt(1)
	ds_write_b128 v14, v[48:51] offset:49984
	s_waitcnt vmcnt(0)
	ds_write_b128 v14, v[52:55] offset:58304
	s_waitcnt lgkmcnt(0)
	s_barrier
; __device__ __forceinline__ int otid(int wv) { int t; asm volatile("v_mbcnt_lo_u32_b32 %0, -1, 0\n\tv_mbcnt_hi_u32_b32 %0, -1, %0\n\tv_lshl_add_u32 %0, %1, 6, %0" : "=&v"(t) : "s"(wv)); return t; }
; __device__ __forceinline__ unsigned cvt_pk_bf16(float lo, float hi) { const f2_t v = {lo, hi}; const bf2_t b = __builtin_convertvector(v, bf2_t); return __builtin_bit_cast(unsigned, b); }
; __device__ void convert_matrix(int wv, const float* src, int K, int N, int ld, int perm, bf16_t* dst, float* tileL, int rot) {
;     const int tid = otid(wv), G = gridDim.x, ntk = K >> 6, ntiles = ntk * (N >> 8);
;     for (int t = (blockIdx.x + G - (rot % G)) % G; t < ntiles; t += G) {
;         const int k0 = (t % ntk) * 64, n0 = (t / ntk) * 256;
;     ...
;         { const int n = tid >> 1, kh = (tid & 1) * 32;
; #pragma unroll
;             for (int q = 0; q < 4; ++q) { float e[8];
; #pragma unroll
;                 for (int j = 0; j < 8; ++j) e[j] = tileL[(kh + 8 * q + j) * 257 + n];
;                 u32x4 w; w.x = cvt_pk_bf16(e[0], e[1]); w.y = cvt_pk_bf16(e[2], e[3]); w.z = cvt_pk_bf16(e[4], e[5]); w.w = cvt_pk_bf16(e[6], e[7]);
;                 *(u32x4*)(dst + (size_t)(n0 + n) * K + k0 + kh + 8 * q) = w; } }
;         __syncthreads();
	ds_read_b32 v23, v22
	ds_read_b32 v24, v22 offset:1040
	ds_read_b32 v25, v22 offset:2080
	ds_read_b32 v26, v22 offset:3120
	ds_read_b32 v27, v22 offset:4160
	ds_read_b32 v28, v22 offset:5200
	ds_read_b32 v29, v22 offset:6240
	ds_read_b32 v30, v22 offset:7280
	ds_read_b32 v31, v22 offset:8320
	ds_read_b32 v32, v22 offset:9360
	ds_read_b32 v33, v22 offset:10400
	ds_read_b32 v34, v22 offset:11440
	ds_read_b32 v35, v22 offset:12480
	ds_read_b32 v36, v22 offset:13520
	ds_read_b32 v37, v22 offset:14560
	ds_read_b32 v38, v22 offset:15600
	ds_read_b32 v39, v22 offset:16640
	ds_read_b32 v40, v22 offset:17680
	ds_read_b32 v41, v22 offset:18720
	ds_read_b32 v42, v22 offset:19760
	ds_read_b32 v43, v22 offset:20800
	ds_read_b32 v44, v22 offset:21840
	ds_read_b32 v45, v22 offset:22880
	ds_read_b32 v46, v22 offset:23920
	ds_read_b32 v47, v22 offset:24960
	ds_read_b32 v48, v22 offset:26000
	ds_read_b32 v49, v22 offset:27040
	ds_read_b32 v50, v22 offset:28080
	ds_read_b32 v51, v22 offset:29120
	ds_read_b32 v52, v22 offset:30160
	ds_read_b32 v53, v22 offset:31200
	ds_read_b32 v54, v22 offset:32240
	s_waitcnt lgkmcnt(14)
	v_cvt_pk_bf16_f32 v24, v23, v24
	v_cvt_pk_bf16_f32 v25, v25, v26
	v_cvt_pk_bf16_f32 v26, v27, v28
	v_cvt_pk_bf16_f32 v27, v29, v30
	v_cvt_pk_bf16_f32 v28, v31, v32
	v_cvt_pk_bf16_f32 v29, v33, v34
	v_cvt_pk_bf16_f32 v30, v35, v36
	v_cvt_pk_bf16_f32 v31, v37, v38
	v_cvt_pk_bf16_f32 v32, v39, v40
	s_waitcnt lgkmcnt(12)
	v_cvt_pk_bf16_f32 v33, v41, v42
	s_waitcnt lgkmcnt(10)
	v_cvt_pk_bf16_f32 v34, v43, v44
	s_waitcnt lgkmcnt(8)
	v_cvt_pk_bf16_f32 v35, v45, v46
	s_waitcnt lgkmcnt(6)
	v_cvt_pk_bf16_f32 v36, v47, v48
	s_waitcnt lgkmcnt(4)
	v_cvt_pk_bf16_f32 v37, v49, v50
	s_waitcnt lgkmcnt(2)
	v_cvt_pk_bf16_f32 v38, v51, v52
	s_waitcnt lgkmcnt(0)
	v_cvt_pk_bf16_f32 v39, v53, v54
	global_store_dwordx4 v[56:57], v[24:27], off
	global_store_dwordx4 v[56:57], v[28:31], off offset:16
	global_store_dwordx4 v[56:57], v[32:35], off offset:32
	global_store_dwordx4 v[56:57], v[36:39], off offset:48
	s_barrier
	s_cbranch_scc1 .LBB0_35
.LBB0_36:
	v_readlane_b32 s44, v253, 17
	v_readlane_b32 s58, v253, 31
	v_readlane_b32 s59, v253, 32
	s_add_u32 s0, s58, 0x800000
	s_addc_u32 s1, s59, 0
	s_abs_i32 s39, s34
	v_cvt_f32_u32_e32 v2, s39
	s_sub_i32 s4, 0, s39
	v_readlane_b32 s45, v253, 18
	v_readlane_b32 s46, v253, 19
	v_rcp_iflag_f32_e32 v2, v2
	v_readlane_b32 s47, v253, 20
	v_readlane_b32 s48, v253, 21
	v_readlane_b32 s49, v253, 22
	v_mul_f32_e32 v2, 0x4f7ffffe, v2
	v_cvt_u32_f32_e32 v2, v2
	v_readlane_b32 s50, v253, 23
	v_readlane_b32 s51, v253, 24
	v_readlane_b32 s52, v253, 25
	v_readfirstlane_b32 s40, v2
	s_mul_i32 s4, s4, s40
	s_mul_hi_u32 s4, s40, s4
	s_add_i32 s40, s40, s4
	s_lshr_b32 s4, s40, 25
	s_mul_i32 s4, s4, s39
	s_sub_i32 s4, 0x80, s4
	s_sub_i32 s5, s4, s39
	s_cmp_ge_u32 s4, s39
	s_cselect_b32 s4, s5, s4
	s_sub_i32 s5, s4, s39
	s_cmp_ge_u32 s4, s39
	s_cselect_b32 s4, s5, s4
	s_sub_i32 s4, s3, s4
	s_mul_hi_u32 s5, s4, s38
	s_mul_i32 s5, s5, s34
	s_sub_i32 s4, s4, s5
	s_sub_i32 s5, s4, s34
	s_cmp_ge_u32 s4, s34
	s_cselect_b32 s4, s5, s4
	s_sub_i32 s5, s4, s34
	s_cmp_ge_u32 s4, s34
	s_cselect_b32 s12, s5, s4
	s_cmpk_gt_i32 s12, 0x7f
	v_readlane_b32 s53, v253, 26
	v_readlane_b32 s54, v253, 27
	v_readlane_b32 s55, v253, 28
	v_readlane_b32 s56, v253, 29
	v_readlane_b32 s57, v253, 30
	v_mbcnt_lo_u32_b32 v2, -1, 0
	v_mbcnt_hi_u32_b32 v2, -1, v2
	v_lshl_add_u32 v2, s33, 6, v2
	s_cbranch_scc1 .LBB0_39
	v_lshlrev_b32_e32 v3, 2, v2
	v_and_b32_e32 v4, 0xfc, v3
	v_ashrrev_i32_e32 v5, 1, v2
	v_lshlrev_b32_e32 v3, 5, v2
	v_ashrrev_i32_e32 v6, 6, v2
	v_add_u32_e32 v7, 0x200, v2
	v_add_u32_e32 v8, 0x400, v2
	v_add_u32_e32 v9, 0x600, v2
	v_add_u32_e32 v10, 0x800, v2
	v_add_u32_e32 v11, 0xa00, v2
	v_add_u32_e32 v12, 0xc00, v2
	v_add_u32_e32 v2, 0xe00, v2
	v_and_b32_e32 v22, 32, v3
	s_movk_i32 s8, 0x404
	v_ashrrev_i32_e32 v7, 6, v7
	v_ashrrev_i32_e32 v8, 6, v8
	v_ashrrev_i32_e32 v9, 6, v9
	v_ashrrev_i32_e32 v10, 6, v10
	v_ashrrev_i32_e32 v11, 6, v11
	v_ashrrev_i32_e32 v12, 6, v12
	v_ashrrev_i32_e32 v13, 6, v2
	s_add_u32 s4, s41, 0xfec600
	v_lshl_add_u32 v21, v4, 2, 0
	v_lshl_add_u32 v23, v5, 2, 0
	v_mul_u32_u24_e32 v24, 0x412, v22
	v_mul_lo_u32 v2, v6, s8
	v_mul_lo_u32 v15, v7, s8
	v_mul_lo_u32 v16, v8, s8
	v_mul_lo_u32 v17, v9, s8
	v_mul_lo_u32 v18, v10, s8
	v_mul_lo_u32 v19, v11, s8
	v_mul_lo_u32 v20, v12, s8
	v_mul_lo_u32 v25, v13, s8
	s_addc_u32 s5, s42, 0
	v_mov_b32_e32 v3, 0
	s_lshl_b32 s10, s12, 6
	s_lshl_b32 s11, s34, 6
	v_add_u32_e32 v14, v21, v2
	v_mad_u32_u24 v14, v6, 12, v14
	v_add_u32_e32 v15, v21, v15
	v_add_u32_e32 v16, v21, v16
	v_add_u32_e32 v17, v21, v17
	v_add_u32_e32 v18, v21, v18
	v_add_u32_e32 v19, v21, v19
	v_add_u32_e32 v20, v21, v20
	v_add_u32_e32 v21, v21, v25
	v_lshlrev_b32_e32 v2, 1, v22
	v_add_u32_e32 v22, v23, v24
	s_mov_b32 s13, s12
; __device__ __forceinline__ unsigned cvt_pk_bf16(float lo, float hi) { const f2_t v = {lo, hi}; const bf2_t b = __builtin_convertvector(v, bf2_t); return __builtin_bit_cast(unsigned, b); }
; __device__ __forceinline__ int upcol(int n) { return (n >> 8) * 128 + (n & 127) + ((n & 128) ? FFD : 0); }
; __device__ void convert_matrix(int wv, const float* src, int K, int N, int ld, int perm, bf16_t* dst, float* tileL, int rot) {
;     ...
;     for (int t = (blockIdx.x + G - (rot % G)) % G; t < ntiles; t += G) {
;         const int k0 = (t % ntk) * 64, n0 = (t / ntk) * 256;
;         f32x4 v[8];
; #pragma unroll
;         for (int ps = 0; ps < 8; ++ps) { const int idx = tid + ps * NTHR, kk = idx >> 6, n4 = (idx & 63) * 4; const int sc = perm ? upcol(n0 + n4) : n0 + n4;
;             v[ps] = *(const f32x4*)(src + (size_t)(k0 + kk) * ld + sc); }
; #pragma unroll
;         for (int ps = 0; ps < 8; ++ps) { const int idx = tid + ps * NTHR, kk = idx >> 6, n4 = (idx & 63) * 4;
;             float* tp = tileL + kk * 257 + n4; tp[0] = v[ps][0]; tp[1] = v[ps][1]; tp[2] = v[ps][2]; tp[3] = v[ps][3]; }
;         __syncthreads();
;         { const int n = tid >> 1, kh = (tid & 1) * 32;
; #pragma unroll
;             for (int q = 0; q < 4; ++q) { float e[8];
; #pragma unroll
;                 for (int j = 0; j < 8; ++j) e[j] = tileL[(kh + 8 * q + j) * 257 + n];
;                 u32x4 w; w.x = cvt_pk_bf16(e[0], e[1]); w.y = cvt_pk_bf16(e[2], e[3]); w.z = cvt_pk_bf16(e[4], e[5]); w.w = cvt_pk_bf16(e[6], e[7]);
;                 *(u32x4*)(dst + (size_t)(n0 + n) * K + k0 + kh + 8 * q) = w; } }
.LBB0_38:
	s_ashr_i32 s8, s13, 31
	s_lshr_b32 s8, s8, 28
	s_add_i32 s8, s13, s8
	s_ashr_i32 s8, s8, 4
	s_lshl_b32 s14, s8, 10
	s_lshl_b32 s9, s8, 8
	s_sub_i32 s8, s10, s14
	v_add_u32_e32 v26, s8, v6
	v_add_u32_e32 v28, s8, v7
	v_add_u32_e32 v30, s8, v8
	v_add_u32_e32 v32, s8, v9
	v_add_u32_e32 v34, s8, v10
	v_add_u32_e32 v36, s8, v11
	v_add_u32_e32 v38, s8, v12
	v_add_u32_e32 v40, s8, v13
	v_or_b32_e32 v24, s9, v4
	v_ashrrev_i32_e32 v27, 31, v26
	v_ashrrev_i32_e32 v29, 31, v28
	v_ashrrev_i32_e32 v31, 31, v30
	v_ashrrev_i32_e32 v33, 31, v32
	v_ashrrev_i32_e32 v35, 31, v34
	v_ashrrev_i32_e32 v37, 31, v36
	v_ashrrev_i32_e32 v39, 31, v38
	v_ashrrev_i32_e32 v41, 31, v40
	v_ashrrev_i32_e32 v25, 31, v24
	v_lshlrev_b64 v[26:27], 13, v[26:27]
	v_lshlrev_b64 v[28:29], 13, v[28:29]
	v_lshlrev_b64 v[30:31], 13, v[30:31]
	v_lshlrev_b64 v[32:33], 13, v[32:33]
	v_lshlrev_b64 v[34:35], 13, v[34:35]
	v_lshlrev_b64 v[36:37], 13, v[36:37]
	v_lshlrev_b64 v[38:39], 13, v[38:39]
	v_lshlrev_b64 v[40:41], 13, v[40:41]
	v_lshlrev_b64 v[24:25], 2, v[24:25]
	v_lshl_add_u64 v[26:27], s[0:1], 0, v[26:27]
	v_lshl_add_u64 v[28:29], s[0:1], 0, v[28:29]
	v_lshl_add_u64 v[30:31], s[0:1], 0, v[30:31]
	v_lshl_add_u64 v[32:33], s[0:1], 0, v[32:33]
	v_lshl_add_u64 v[34:35], s[0:1], 0, v[34:35]
	v_lshl_add_u64 v[36:37], s[0:1], 0, v[36:37]
	v_lshl_add_u64 v[38:39], s[0:1], 0, v[38:39]
	v_lshl_add_u64 v[40:41], s[0:1], 0, v[40:41]
	v_lshl_add_u64 v[26:27], v[26:27], 0, v[24:25]
	v_lshl_add_u64 v[28:29], v[28:29], 0, v[24:25]
	v_lshl_add_u64 v[42:43], v[30:31], 0, v[24:25]
	v_lshl_add_u64 v[44:45], v[32:33], 0, v[24:25]
	v_lshl_add_u64 v[46:47], v[34:35], 0, v[24:25]
	v_lshl_add_u64 v[48:49], v[36:37], 0, v[24:25]
	v_lshl_add_u64 v[50:51], v[38:39], 0, v[24:25]
	v_lshl_add_u64 v[52:53], v[40:41], 0, v[24:25]
	global_load_dwordx4 v[24:27], v[26:27], off
	s_nop 0
	global_load_dwordx4 v[28:31], v[28:29], off
	s_nop 0
	global_load_dwordx4 v[32:35], v[42:43], off
	global_load_dwordx4 v[36:39], v[44:45], off
	s_nop 0
	global_load_dwordx4 v[40:43], v[46:47], off
	s_nop 0
	global_load_dwordx4 v[44:47], v[48:49], off
	s_nop 0
	global_load_dwordx4 v[48:51], v[50:51], off
	s_nop 0
	global_load_dwordx4 v[52:55], v[52:53], off
	v_add_u32_e32 v56, s9, v5
	v_ashrrev_i32_e32 v57, 31, v56
	v_lshlrev_b64 v[56:57], 11, v[56:57]
	s_ashr_i32 s9, s8, 31
	v_lshl_add_u64 v[56:57], s[4:5], 0, v[56:57]
	s_add_i32 s13, s13, s34
	s_add_i32 s10, s10, s11
	v_lshl_add_u64 v[56:57], s[8:9], 1, v[56:57]
	s_cmpk_lt_i32 s13, 0x80
	v_lshl_add_u64 v[56:57], v[56:57], 0, v[2:3]
	s_waitcnt vmcnt(7)
	ds_write_b128 v14, v[24:27]
	s_waitcnt vmcnt(6)
	ds_write_b128 v14, v[28:31] offset:8320
	s_waitcnt vmcnt(5)
	ds_write_b128 v14, v[32:35] offset:16640
	s_waitcnt vmcnt(4)
	ds_write_b128 v14, v[36:39] offset:24960
	s_waitcnt vmcnt(3)
	ds_write_b128 v14, v[40:43] offset:33344
	s_waitcnt vmcnt(2)
	ds_write_b128 v14, v[44:47] offset:41664
	s_waitcnt vmcnt(1)
	ds_write_b128 v14, v[48:51] offset:49984
	s_waitcnt vmcnt(0)
	ds_write_b128 v14, v[52:55] offset:58304
	s_waitcnt lgkmcnt(0)
	s_barrier
	ds_read_b32 v23, v22
	ds_read_b32 v24, v22 offset:1040
	ds_read_b32 v25, v22 offset:2080
	ds_read_b32 v26, v22 offset:3120
	ds_read_b32 v27, v22 offset:4160
	ds_read_b32 v28, v22 offset:5200
	ds_read_b32 v29, v22 offset:6240
	ds_read_b32 v30, v22 offset:7280
	ds_read_b32 v31, v22 offset:8320
	ds_read_b32 v32, v22 offset:9360
	ds_read_b32 v33, v22 offset:10400
	ds_read_b32 v34, v22 offset:11440
	ds_read_b32 v35, v22 offset:12480
	ds_read_b32 v36, v22 offset:13520
	ds_read_b32 v37, v22 offset:14560
	ds_read_b32 v38, v22 offset:15600
	ds_read_b32 v39, v22 offset:16640
	ds_read_b32 v40, v22 offset:17680
	ds_read_b32 v41, v22 offset:18720
	ds_read_b32 v42, v22 offset:19760
	ds_read_b32 v43, v22 offset:20800
	ds_read_b32 v44, v22 offset:21840
	ds_read_b32 v45, v22 offset:22880
	ds_read_b32 v46, v22 offset:23920
	ds_read_b32 v47, v22 offset:24960
	ds_read_b32 v48, v22 offset:26000
	ds_read_b32 v49, v22 offset:27040
	ds_read_b32 v50, v22 offset:28080
	ds_read_b32 v51, v22 offset:29120
	ds_read_b32 v52, v22 offset:30160
	ds_read_b32 v53, v22 offset:31200
	ds_read_b32 v54, v22 offset:32240
	s_waitcnt lgkmcnt(14)
	v_cvt_pk_bf16_f32 v24, v23, v24
	v_cvt_pk_bf16_f32 v25, v25, v26
	v_cvt_pk_bf16_f32 v26, v27, v28
	v_cvt_pk_bf16_f32 v27, v29, v30
	v_cvt_pk_bf16_f32 v28, v31, v32
	v_cvt_pk_bf16_f32 v29, v33, v34
	v_cvt_pk_bf16_f32 v30, v35, v36
	v_cvt_pk_bf16_f32 v31, v37, v38
	v_cvt_pk_bf16_f32 v32, v39, v40
	s_waitcnt lgkmcnt(12)
	v_cvt_pk_bf16_f32 v33, v41, v42
	s_waitcnt lgkmcnt(10)
	v_cvt_pk_bf16_f32 v34, v43, v44
	s_waitcnt lgkmcnt(8)
	v_cvt_pk_bf16_f32 v35, v45, v46
	s_waitcnt lgkmcnt(6)
	v_cvt_pk_bf16_f32 v36, v47, v48
	s_waitcnt lgkmcnt(4)
	v_cvt_pk_bf16_f32 v37, v49, v50
	s_waitcnt lgkmcnt(2)
	v_cvt_pk_bf16_f32 v38, v51, v52
	s_waitcnt lgkmcnt(0)
	v_cvt_pk_bf16_f32 v39, v53, v54
	global_store_dwordx4 v[56:57], v[24:27], off
	global_store_dwordx4 v[56:57], v[28:31], off offset:16
	global_store_dwordx4 v[56:57], v[32:35], off offset:32
	global_store_dwordx4 v[56:57], v[36:39], off offset:48
	s_barrier
	s_cbranch_scc1 .LBB0_38
; __device__ __forceinline__ int otid(int wv) { int t; asm volatile("v_mbcnt_lo_u32_b32 %0, -1, 0\n\tv_mbcnt_hi_u32_b32 %0, -1, %0\n\tv_lshl_add_u32 %0, %1, 6, %0" : "=&v"(t) : "s"(wv)); return t; }
; __device__ __forceinline__ int upcol(int n) { return (n >> 8) * 128 + (n & 127) + ((n & 128) ? FFD : 0); }
; __device__ void convert_matrix(int wv, const float* src, int K, int N, int ld, int perm, bf16_t* dst, float* tileL, int rot) {
;     const int tid = otid(wv), G = gridDim.x, ntk = K >> 6, ntiles = ntk * (N >> 8);
;     for (int t = (blockIdx.x + G - (rot % G)) % G; t < ntiles; t += G) {
;         const int k0 = (t % ntk) * 64, n0 = (t / ntk) * 256;
;         f32x4 v[8];
; #pragma unroll
;         for (int ps = 0; ps < 8; ++ps) { const int idx = tid + ps * NTHR, kk = idx >> 6, n4 = (idx & 63) * 4; const int sc = perm ? upcol(n0 + n4) : n0 + n4;
;             v[ps] = *(const f32x4*)(src + (size_t)(k0 + kk) * ld + sc); }
; #pragma unroll
;         for (int ps = 0; ps < 8; ++ps) { const int idx = tid + ps * NTHR, kk = idx >> 6, n4 = (idx & 63) * 4;
;             float* tp = tileL + kk * 257 + n4; tp[0] = v[ps][0]; tp[1] = v[ps][1]; tp[2] = v[ps][2]; tp[3] = v[ps][3]; }
;         __syncthreads();
.LBB0_39:
	v_readlane_b32 s4, v253, 33
	s_cmp_gt_i32 s4, 63
	v_mbcnt_lo_u32_b32 v2, -1, 0
	v_mbcnt_hi_u32_b32 v2, -1, v2
	v_lshl_add_u32 v2, s33, 6, v2
	s_cbranch_scc1 .LBB0_42
	v_lshlrev_b32_e32 v3, 2, v2
	v_and_b32_e32 v4, 0xfc, v3
	v_ashrrev_i32_e32 v5, 1, v2
	v_lshlrev_b32_e32 v3, 5, v2
	v_ashrrev_i32_e32 v6, 6, v2
	v_add_u32_e32 v7, 0x200, v2
	v_add_u32_e32 v8, 0x400, v2
	v_add_u32_e32 v9, 0x600, v2
	v_add_u32_e32 v10, 0x800, v2
	v_add_u32_e32 v11, 0xa00, v2
	v_add_u32_e32 v12, 0xc00, v2
	v_add_u32_e32 v2, 0xe00, v2
	v_and_b32_e32 v22, 32, v3
	s_movk_i32 s8, 0x404
	v_ashrrev_i32_e32 v7, 6, v7
	v_ashrrev_i32_e32 v8, 6, v8
	v_ashrrev_i32_e32 v9, 6, v9
	v_ashrrev_i32_e32 v10, 6, v10
	v_ashrrev_i32_e32 v11, 6, v11
	v_ashrrev_i32_e32 v12, 6, v12
	v_ashrrev_i32_e32 v13, 6, v2
	s_add_u32 s4, s41, 0x13ec600
	v_lshl_add_u32 v21, v4, 2, 0
	v_lshl_add_u32 v23, v5, 2, 0
	v_mul_u32_u24_e32 v24, 0x412, v22
	v_mul_lo_u32 v2, v6, s8
	v_mul_lo_u32 v15, v7, s8
	v_mul_lo_u32 v16, v8, s8
	v_mul_lo_u32 v17, v9, s8
	v_mul_lo_u32 v18, v10, s8
	v_mul_lo_u32 v19, v11, s8
	v_mul_lo_u32 v20, v12, s8
	v_mul_lo_u32 v25, v13, s8
	v_readlane_b32 s13, v253, 33
	v_readlane_b32 s44, v253, 1
	s_addc_u32 s5, s42, 0
	v_mov_b32_e32 v3, 0
	s_lshl_b32 s10, s13, 6
	s_lshl_b32 s11, s34, 6
	v_add_u32_e32 v14, v21, v2
	v_mad_u32_u24 v14, v6, 12, v14
	v_add_u32_e32 v15, v21, v15
	v_add_u32_e32 v16, v21, v16
	v_add_u32_e32 v17, v21, v17
	v_add_u32_e32 v18, v21, v18
	v_add_u32_e32 v19, v21, v19
	v_add_u32_e32 v20, v21, v20
	v_add_u32_e32 v21, v21, v25
	v_lshlrev_b32_e32 v2, 1, v22
	v_add_u32_e32 v22, v23, v24
	v_readlane_b32 s50, v253, 7
	v_readlane_b32 s51, v253, 8
	v_readlane_b32 s45, v253, 2
	v_readlane_b32 s46, v253, 3
	v_readlane_b32 s47, v253, 4
	v_readlane_b32 s48, v253, 5
	v_readlane_b32 s49, v253, 6
	v_readlane_b32 s52, v253, 9
	v_readlane_b32 s53, v253, 10
	v_readlane_b32 s54, v253, 11
	v_readlane_b32 s55, v253, 12
	v_readlane_b32 s56, v253, 13
	v_readlane_b32 s57, v253, 14
	v_readlane_b32 s58, v253, 15
	v_readlane_b32 s59, v253, 16
.LBB0_41:
	s_ashr_i32 s8, s13, 31
	s_lshr_b32 s8, s8, 28
	s_add_i32 s8, s13, s8
	s_ashr_i32 s8, s8, 4
	s_lshl_b32 s14, s8, 10
	s_lshl_b32 s9, s8, 8
	s_sub_i32 s8, s10, s14
	v_add_u32_e32 v26, s8, v6
	v_add_u32_e32 v28, s8, v7
	v_add_u32_e32 v30, s8, v8
	v_add_u32_e32 v32, s8, v9
	v_add_u32_e32 v34, s8, v10
	v_add_u32_e32 v36, s8, v11
	v_add_u32_e32 v38, s8, v12
	v_add_u32_e32 v40, s8, v13
	v_or_b32_e32 v24, s9, v4
	v_ashrrev_i32_e32 v27, 31, v26
	v_ashrrev_i32_e32 v29, 31, v28
	v_ashrrev_i32_e32 v31, 31, v30
	v_ashrrev_i32_e32 v33, 31, v32
	v_ashrrev_i32_e32 v35, 31, v34
	v_ashrrev_i32_e32 v37, 31, v36
	v_ashrrev_i32_e32 v39, 31, v38
	v_ashrrev_i32_e32 v41, 31, v40
	v_ashrrev_i32_e32 v25, 31, v24
	v_lshlrev_b64 v[26:27], 12, v[26:27]
	v_lshlrev_b64 v[28:29], 12, v[28:29]
	v_lshlrev_b64 v[30:31], 12, v[30:31]
	v_lshlrev_b64 v[32:33], 12, v[32:33]
	v_lshlrev_b64 v[34:35], 12, v[34:35]
	v_lshlrev_b64 v[36:37], 12, v[36:37]
	v_lshlrev_b64 v[38:39], 12, v[38:39]
	v_lshlrev_b64 v[40:41], 12, v[40:41]
	v_lshlrev_b64 v[24:25], 2, v[24:25]
	v_lshl_add_u64 v[26:27], s[50:51], 0, v[26:27]
	v_lshl_add_u64 v[28:29], s[50:51], 0, v[28:29]
	v_lshl_add_u64 v[30:31], s[50:51], 0, v[30:31]
	v_lshl_add_u64 v[32:33], s[50:51], 0, v[32:33]
	v_lshl_add_u64 v[34:35], s[50:51], 0, v[34:35]
	v_lshl_add_u64 v[36:37], s[50:51], 0, v[36:37]
	v_lshl_add_u64 v[38:39], s[50:51], 0, v[38:39]
	v_lshl_add_u64 v[40:41], s[50:51], 0, v[40:41]
	v_lshl_add_u64 v[26:27], v[26:27], 0, v[24:25]
	v_lshl_add_u64 v[28:29], v[28:29], 0, v[24:25]
	v_lshl_add_u64 v[42:43], v[30:31], 0, v[24:25]
	v_lshl_add_u64 v[44:45], v[32:33], 0, v[24:25]
	v_lshl_add_u64 v[46:47], v[34:35], 0, v[24:25]
	v_lshl_add_u64 v[48:49], v[36:37], 0, v[24:25]
	v_lshl_add_u64 v[50:51], v[38:39], 0, v[24:25]
	v_lshl_add_u64 v[52:53], v[40:41], 0, v[24:25]
	global_load_dwordx4 v[24:27], v[26:27], off
	s_nop 0
	global_load_dwordx4 v[28:31], v[28:29], off
	s_nop 0
	global_load_dwordx4 v[32:35], v[42:43], off
	global_load_dwordx4 v[36:39], v[44:45], off
	s_nop 0
	global_load_dwordx4 v[40:43], v[46:47], off
	s_nop 0
	global_load_dwordx4 v[44:47], v[48:49], off
	s_nop 0
	global_load_dwordx4 v[48:51], v[50:51], off
	s_nop 0
	global_load_dwordx4 v[52:55], v[52:53], off
	v_add_u32_e32 v56, s9, v5
	v_ashrrev_i32_e32 v57, 31, v56
	v_lshlrev_b64 v[56:57], 11, v[56:57]
	s_ashr_i32 s9, s8, 31
	v_lshl_add_u64 v[56:57], s[4:5], 0, v[56:57]
	s_add_i32 s13, s13, s34
	s_add_i32 s10, s10, s11
	v_lshl_add_u64 v[56:57], s[8:9], 1, v[56:57]
	s_cmp_lt_i32 s13, 64
	v_lshl_add_u64 v[56:57], v[56:57], 0, v[2:3]
	s_waitcnt vmcnt(7)
	ds_write_b128 v14, v[24:27]
	s_waitcnt vmcnt(6)
	ds_write_b128 v14, v[28:31] offset:8320
	s_waitcnt vmcnt(5)
	ds_write_b128 v14, v[32:35] offset:16640
	s_waitcnt vmcnt(4)
	ds_write_b128 v14, v[36:39] offset:24960
	s_waitcnt vmcnt(3)
	ds_write_b128 v14, v[40:43] offset:33344
	s_waitcnt vmcnt(2)
	ds_write_b128 v14, v[44:47] offset:41664
	s_waitcnt vmcnt(1)
	ds_write_b128 v14, v[48:51] offset:49984
	s_waitcnt vmcnt(0)
	ds_write_b128 v14, v[52:55] offset:58304
	s_waitcnt lgkmcnt(0)
	s_barrier
; __device__ __forceinline__ int otid(int wv) { int t; asm volatile("v_mbcnt_lo_u32_b32 %0, -1, 0\n\tv_mbcnt_hi_u32_b32 %0, -1, %0\n\tv_lshl_add_u32 %0, %1, 6, %0" : "=&v"(t) : "s"(wv)); return t; }
; __device__ __forceinline__ unsigned cvt_pk_bf16(float lo, float hi) { const f2_t v = {lo, hi}; const bf2_t b = __builtin_convertvector(v, bf2_t); return __builtin_bit_cast(unsigned, b); }
; __device__ void convert_matrix(int wv, const float* src, int K, int N, int ld, int perm, bf16_t* dst, float* tileL, int rot) {
;     const int tid = otid(wv), G = gridDim.x, ntk = K >> 6, ntiles = ntk * (N >> 8);
;     for (int t = (blockIdx.x + G - (rot % G)) % G; t < ntiles; t += G) {
;         const int k0 = (t % ntk) * 64, n0 = (t / ntk) * 256;
;     ...
;         { const int n = tid >> 1, kh = (tid & 1) * 32;
; #pragma unroll
;             for (int q = 0; q < 4; ++q) { float e[8];
; #pragma unroll
;                 for (int j = 0; j < 8; ++j) e[j] = tileL[(kh + 8 * q + j) * 257 + n];
;                 u32x4 w; w.x = cvt_pk_bf16(e[0], e[1]); w.y = cvt_pk_bf16(e[2], e[3]); w.z = cvt_pk_bf16(e[4], e[5]); w.w = cvt_pk_bf16(e[6], e[7]);
;                 *(u32x4*)(dst + (size_t)(n0 + n) * K + k0 + kh + 8 * q) = w; } }
;         __syncthreads();
	ds_read_b32 v23, v22
	ds_read_b32 v24, v22 offset:1040
	ds_read_b32 v25, v22 offset:2080
	ds_read_b32 v26, v22 offset:3120
	ds_read_b32 v27, v22 offset:4160
	ds_read_b32 v28, v22 offset:5200
	ds_read_b32 v29, v22 offset:6240
	ds_read_b32 v30, v22 offset:7280
	ds_read_b32 v31, v22 offset:8320
	ds_read_b32 v32, v22 offset:9360
	ds_read_b32 v33, v22 offset:10400
	ds_read_b32 v34, v22 offset:11440
	ds_read_b32 v35, v22 offset:12480
	ds_read_b32 v36, v22 offset:13520
	ds_read_b32 v37, v22 offset:14560
	ds_read_b32 v38, v22 offset:15600
	ds_read_b32 v39, v22 offset:16640
	ds_read_b32 v40, v22 offset:17680
	ds_read_b32 v41, v22 offset:18720
	ds_read_b32 v42, v22 offset:19760
	ds_read_b32 v43, v22 offset:20800
	ds_read_b32 v44, v22 offset:21840
	ds_read_b32 v45, v22 offset:22880
	ds_read_b32 v46, v22 offset:23920
	ds_read_b32 v47, v22 offset:24960
	ds_read_b32 v48, v22 offset:26000
	ds_read_b32 v49, v22 offset:27040
	ds_read_b32 v50, v22 offset:28080
	ds_read_b32 v51, v22 offset:29120
	ds_read_b32 v52, v22 offset:30160
	ds_read_b32 v53, v22 offset:31200
	ds_read_b32 v54, v22 offset:32240
	s_waitcnt lgkmcnt(14)
	v_cvt_pk_bf16_f32 v24, v23, v24
	v_cvt_pk_bf16_f32 v25, v25, v26
	v_cvt_pk_bf16_f32 v26, v27, v28
	v_cvt_pk_bf16_f32 v27, v29, v30
	v_cvt_pk_bf16_f32 v28, v31, v32
	v_cvt_pk_bf16_f32 v29, v33, v34
	v_cvt_pk_bf16_f32 v30, v35, v36
	v_cvt_pk_bf16_f32 v31, v37, v38
	v_cvt_pk_bf16_f32 v32, v39, v40
	s_waitcnt lgkmcnt(12)
	v_cvt_pk_bf16_f32 v33, v41, v42
	s_waitcnt lgkmcnt(10)
	v_cvt_pk_bf16_f32 v34, v43, v44
	s_waitcnt lgkmcnt(8)
	v_cvt_pk_bf16_f32 v35, v45, v46
	s_waitcnt lgkmcnt(6)
	v_cvt_pk_bf16_f32 v36, v47, v48
	s_waitcnt lgkmcnt(4)
	v_cvt_pk_bf16_f32 v37, v49, v50
	s_waitcnt lgkmcnt(2)
	v_cvt_pk_bf16_f32 v38, v51, v52
	s_waitcnt lgkmcnt(0)
	v_cvt_pk_bf16_f32 v39, v53, v54
	global_store_dwordx4 v[56:57], v[24:27], off
	global_store_dwordx4 v[56:57], v[28:31], off offset:16
	global_store_dwordx4 v[56:57], v[32:35], off offset:32
	global_store_dwordx4 v[56:57], v[36:39], off offset:48
	s_barrier
	s_cbranch_scc1 .LBB0_41
.LBB0_42:
	s_lshr_b32 s4, s40, 26
	s_mul_i32 s4, s4, s39
	s_sub_i32 s4, 64, s4
	s_sub_i32 s5, s4, s39
	s_cmp_ge_u32 s4, s39
	s_cselect_b32 s4, s5, s4
	s_sub_i32 s5, s4, s39
	s_cmp_ge_u32 s4, s39
	s_cselect_b32 s4, s5, s4
	s_sub_i32 s4, s3, s4
	s_mul_hi_u32 s5, s4, s38
	s_mul_i32 s5, s5, s34
	s_sub_i32 s4, s4, s5
	s_sub_i32 s5, s4, s34
	s_cmp_ge_u32 s4, s34
	s_cselect_b32 s4, s5, s4
	s_sub_i32 s5, s4, s34
	s_cmp_ge_u32 s4, s34
	s_cselect_b32 s13, s5, s4
	s_cmp_gt_i32 s13, 63
	v_mbcnt_lo_u32_b32 v2, -1, 0
	v_mbcnt_hi_u32_b32 v2, -1, v2
	v_lshl_add_u32 v2, s33, 6, v2
	s_cbranch_scc1 .LBB0_45
	v_readlane_b32 s44, v253, 1
	v_readlane_b32 s50, v253, 7
	v_lshlrev_b32_e32 v3, 2, v2
	v_readlane_b32 s51, v253, 8
	s_add_u32 s4, s50, 0x400000
	v_and_b32_e32 v4, 0xfc, v3
	v_ashrrev_i32_e32 v5, 1, v2
	v_lshlrev_b32_e32 v3, 5, v2
	v_ashrrev_i32_e32 v6, 6, v2
	v_add_u32_e32 v7, 0x200, v2
	v_add_u32_e32 v8, 0x400, v2
	v_add_u32_e32 v9, 0x600, v2
	v_add_u32_e32 v10, 0x800, v2
	v_add_u32_e32 v11, 0xa00, v2
	v_add_u32_e32 v12, 0xc00, v2
	v_add_u32_e32 v2, 0xe00, v2
	s_addc_u32 s5, s51, 0
	v_and_b32_e32 v22, 32, v3
	s_movk_i32 s10, 0x404
	v_ashrrev_i32_e32 v7, 6, v7
	v_ashrrev_i32_e32 v8, 6, v8
	v_ashrrev_i32_e32 v9, 6, v9
	v_ashrrev_i32_e32 v10, 6, v10
	v_ashrrev_i32_e32 v11, 6, v11
	v_ashrrev_i32_e32 v12, 6, v12
	v_ashrrev_i32_e32 v13, 6, v2
	s_add_u32 s8, s41, 0x15ec600
	v_lshl_add_u32 v21, v4, 2, 0
	v_lshl_add_u32 v23, v5, 2, 0
	v_mul_u32_u24_e32 v24, 0x412, v22
	v_mul_lo_u32 v2, v6, s10
	v_mul_lo_u32 v15, v7, s10
	v_mul_lo_u32 v16, v8, s10
	v_mul_lo_u32 v17, v9, s10
	v_mul_lo_u32 v18, v10, s10
	v_mul_lo_u32 v19, v11, s10
	v_mul_lo_u32 v20, v12, s10
	v_mul_lo_u32 v25, v13, s10
	s_addc_u32 s9, s42, 0
	v_mov_b32_e32 v3, 0
	s_lshl_b32 s14, s13, 6
	s_lshl_b32 s15, s34, 6
	v_add_u32_e32 v14, v21, v2
	v_mad_u32_u24 v14, v6, 12, v14
	v_add_u32_e32 v15, v21, v15
	v_add_u32_e32 v16, v21, v16
	v_add_u32_e32 v17, v21, v17
	v_add_u32_e32 v18, v21, v18
	v_add_u32_e32 v19, v21, v19
	v_add_u32_e32 v20, v21, v20
	v_add_u32_e32 v21, v21, v25
	v_lshlrev_b32_e32 v2, 1, v22
	v_add_u32_e32 v22, v23, v24
	v_readlane_b32 s45, v253, 2
	v_readlane_b32 s46, v253, 3
	v_readlane_b32 s47, v253, 4
	v_readlane_b32 s48, v253, 5
	v_readlane_b32 s49, v253, 6
	v_readlane_b32 s52, v253, 9
	v_readlane_b32 s53, v253, 10
	v_readlane_b32 s54, v253, 11
	v_readlane_b32 s55, v253, 12
	v_readlane_b32 s56, v253, 13
	v_readlane_b32 s57, v253, 14
	v_readlane_b32 s58, v253, 15
	v_readlane_b32 s59, v253, 16
; __device__ __forceinline__ unsigned cvt_pk_bf16(float lo, float hi) { const f2_t v = {lo, hi}; const bf2_t b = __builtin_convertvector(v, bf2_t); return __builtin_bit_cast(unsigned, b); }
; __device__ __forceinline__ int upcol(int n) { return (n >> 8) * 128 + (n & 127) + ((n & 128) ? FFD : 0); }
; __device__ void convert_matrix(int wv, const float* src, int K, int N, int ld, int perm, bf16_t* dst, float* tileL, int rot) {
;     ...
;     for (int t = (blockIdx.x + G - (rot % G)) % G; t < ntiles; t += G) {
;         const int k0 = (t % ntk) * 64, n0 = (t / ntk) * 256;
;         f32x4 v[8];
; #pragma unroll
;         for (int ps = 0; ps < 8; ++ps) { const int idx = tid + ps * NTHR, kk = idx >> 6, n4 = (idx & 63) * 4; const int sc = perm ? upcol(n0 + n4) : n0 + n4;
;             v[ps] = *(const f32x4*)(src + (size_t)(k0 + kk) * ld + sc); }
; #pragma unroll
;         for (int ps = 0; ps < 8; ++ps) { const int idx = tid + ps * NTHR, kk = idx >> 6, n4 = (idx & 63) * 4;
;             float* tp = tileL + kk * 257 + n4; tp[0] = v[ps][0]; tp[1] = v[ps][1]; tp[2] = v[ps][2]; tp[3] = v[ps][3]; }
;         __syncthreads();
;         { const int n = tid >> 1, kh = (tid & 1) * 32;
; #pragma unroll
;             for (int q = 0; q < 4; ++q) { float e[8];
; #pragma unroll
;                 for (int j = 0; j < 8; ++j) e[j] = tileL[(kh + 8 * q + j) * 257 + n];
;                 u32x4 w; w.x = cvt_pk_bf16(e[0], e[1]); w.y = cvt_pk_bf16(e[2], e[3]); w.z = cvt_pk_bf16(e[4], e[5]); w.w = cvt_pk_bf16(e[6], e[7]);
;                 *(u32x4*)(dst + (size_t)(n0 + n) * K + k0 + kh + 8 * q) = w; } }
.LBB0_44:
	s_ashr_i32 s10, s13, 31
	s_lshr_b32 s10, s10, 28
	s_add_i32 s10, s13, s10
	s_ashr_i32 s10, s10, 4
	s_lshl_b32 s16, s10, 10
	s_lshl_b32 s11, s10, 8
	s_sub_i32 s10, s14, s16
	v_add_u32_e32 v26, s10, v6
	v_add_u32_e32 v28, s10, v7
	v_add_u32_e32 v30, s10, v8
	v_add_u32_e32 v32, s10, v9
	v_add_u32_e32 v34, s10, v10
	v_add_u32_e32 v36, s10, v11
	v_add_u32_e32 v38, s10, v12
	v_add_u32_e32 v40, s10, v13
	v_or_b32_e32 v24, s11, v4
	v_ashrrev_i32_e32 v27, 31, v26
	v_ashrrev_i32_e32 v29, 31, v28
	v_ashrrev_i32_e32 v31, 31, v30
	v_ashrrev_i32_e32 v33, 31, v32
	v_ashrrev_i32_e32 v35, 31, v34
	v_ashrrev_i32_e32 v37, 31, v36
	v_ashrrev_i32_e32 v39, 31, v38
	v_ashrrev_i32_e32 v41, 31, v40
	v_ashrrev_i32_e32 v25, 31, v24
	v_lshlrev_b64 v[26:27], 12, v[26:27]
	v_lshlrev_b64 v[28:29], 12, v[28:29]
	v_lshlrev_b64 v[30:31], 12, v[30:31]
	v_lshlrev_b64 v[32:33], 12, v[32:33]
	v_lshlrev_b64 v[34:35], 12, v[34:35]
	v_lshlrev_b64 v[36:37], 12, v[36:37]
	v_lshlrev_b64 v[38:39], 12, v[38:39]
	v_lshlrev_b64 v[40:41], 12, v[40:41]
	v_lshlrev_b64 v[24:25], 2, v[24:25]
	v_lshl_add_u64 v[26:27], s[4:5], 0, v[26:27]
	v_lshl_add_u64 v[28:29], s[4:5], 0, v[28:29]
	v_lshl_add_u64 v[30:31], s[4:5], 0, v[30:31]
	v_lshl_add_u64 v[32:33], s[4:5], 0, v[32:33]
	v_lshl_add_u64 v[34:35], s[4:5], 0, v[34:35]
	v_lshl_add_u64 v[36:37], s[4:5], 0, v[36:37]
	v_lshl_add_u64 v[38:39], s[4:5], 0, v[38:39]
	v_lshl_add_u64 v[40:41], s[4:5], 0, v[40:41]
	v_lshl_add_u64 v[26:27], v[26:27], 0, v[24:25]
	v_lshl_add_u64 v[28:29], v[28:29], 0, v[24:25]
	v_lshl_add_u64 v[42:43], v[30:31], 0, v[24:25]
	v_lshl_add_u64 v[44:45], v[32:33], 0, v[24:25]
	v_lshl_add_u64 v[46:47], v[34:35], 0, v[24:25]
	v_lshl_add_u64 v[48:49], v[36:37], 0, v[24:25]
	v_lshl_add_u64 v[50:51], v[38:39], 0, v[24:25]
	v_lshl_add_u64 v[52:53], v[40:41], 0, v[24:25]
	global_load_dwordx4 v[24:27], v[26:27], off
	s_nop 0
	global_load_dwordx4 v[28:31], v[28:29], off
	s_nop 0
	global_load_dwordx4 v[32:35], v[42:43], off
	global_load_dwordx4 v[36:39], v[44:45], off
	s_nop 0
	global_load_dwordx4 v[40:43], v[46:47], off
	s_nop 0
	global_load_dwordx4 v[44:47], v[48:49], off
	s_nop 0
	global_load_dwordx4 v[48:51], v[50:51], off
	s_nop 0
	global_load_dwordx4 v[52:55], v[52:53], off
	v_add_u32_e32 v56, s11, v5
	v_ashrrev_i32_e32 v57, 31, v56
	v_lshlrev_b64 v[56:57], 11, v[56:57]
	s_ashr_i32 s11, s10, 31
	v_lshl_add_u64 v[56:57], s[8:9], 0, v[56:57]
	s_add_i32 s13, s13, s34
	s_add_i32 s14, s14, s15
	v_lshl_add_u64 v[56:57], s[10:11], 1, v[56:57]
	s_cmp_lt_i32 s13, 64
	v_lshl_add_u64 v[56:57], v[56:57], 0, v[2:3]
	s_waitcnt vmcnt(7)
	ds_write_b128 v14, v[24:27]
	s_waitcnt vmcnt(6)
	ds_write_b128 v14, v[28:31] offset:8320
	s_waitcnt vmcnt(5)
	ds_write_b128 v14, v[32:35] offset:16640
	s_waitcnt vmcnt(4)
	ds_write_b128 v14, v[36:39] offset:24960
	s_waitcnt vmcnt(3)
	ds_write_b128 v14, v[40:43] offset:33344
	s_waitcnt vmcnt(2)
	ds_write_b128 v14, v[44:47] offset:41664
	s_waitcnt vmcnt(1)
	ds_write_b128 v14, v[48:51] offset:49984
	s_waitcnt vmcnt(0)
	ds_write_b128 v14, v[52:55] offset:58304
	s_waitcnt lgkmcnt(0)
	s_barrier
	ds_read_b32 v23, v22
	ds_read_b32 v24, v22 offset:1040
	ds_read_b32 v25, v22 offset:2080
	ds_read_b32 v26, v22 offset:3120
	ds_read_b32 v27, v22 offset:4160
	ds_read_b32 v28, v22 offset:5200
	ds_read_b32 v29, v22 offset:6240
	ds_read_b32 v30, v22 offset:7280
	ds_read_b32 v31, v22 offset:8320
	ds_read_b32 v32, v22 offset:9360
	ds_read_b32 v33, v22 offset:10400
	ds_read_b32 v34, v22 offset:11440
	ds_read_b32 v35, v22 offset:12480
	ds_read_b32 v36, v22 offset:13520
	ds_read_b32 v37, v22 offset:14560
	ds_read_b32 v38, v22 offset:15600
	ds_read_b32 v39, v22 offset:16640
	ds_read_b32 v40, v22 offset:17680
	ds_read_b32 v41, v22 offset:18720
	ds_read_b32 v42, v22 offset:19760
	ds_read_b32 v43, v22 offset:20800
	ds_read_b32 v44, v22 offset:21840
	ds_read_b32 v45, v22 offset:22880
	ds_read_b32 v46, v22 offset:23920
	ds_read_b32 v47, v22 offset:24960
	ds_read_b32 v48, v22 offset:26000
	ds_read_b32 v49, v22 offset:27040
	ds_read_b32 v50, v22 offset:28080
	ds_read_b32 v51, v22 offset:29120
	ds_read_b32 v52, v22 offset:30160
	ds_read_b32 v53, v22 offset:31200
	ds_read_b32 v54, v22 offset:32240
	s_waitcnt lgkmcnt(14)
	v_cvt_pk_bf16_f32 v24, v23, v24
	v_cvt_pk_bf16_f32 v25, v25, v26
	v_cvt_pk_bf16_f32 v26, v27, v28
	v_cvt_pk_bf16_f32 v27, v29, v30
	v_cvt_pk_bf16_f32 v28, v31, v32
	v_cvt_pk_bf16_f32 v29, v33, v34
	v_cvt_pk_bf16_f32 v30, v35, v36
	v_cvt_pk_bf16_f32 v31, v37, v38
	v_cvt_pk_bf16_f32 v32, v39, v40
	s_waitcnt lgkmcnt(12)
	v_cvt_pk_bf16_f32 v33, v41, v42
	s_waitcnt lgkmcnt(10)
	v_cvt_pk_bf16_f32 v34, v43, v44
	s_waitcnt lgkmcnt(8)
	v_cvt_pk_bf16_f32 v35, v45, v46
	s_waitcnt lgkmcnt(6)
	v_cvt_pk_bf16_f32 v36, v47, v48
	s_waitcnt lgkmcnt(4)
	v_cvt_pk_bf16_f32 v37, v49, v50
	s_waitcnt lgkmcnt(2)
	v_cvt_pk_bf16_f32 v38, v51, v52
	s_waitcnt lgkmcnt(0)
	v_cvt_pk_bf16_f32 v39, v53, v54
	global_store_dwordx4 v[56:57], v[24:27], off
	global_store_dwordx4 v[56:57], v[28:31], off offset:16
	global_store_dwordx4 v[56:57], v[32:35], off offset:32
	global_store_dwordx4 v[56:57], v[36:39], off offset:48
	s_barrier
	s_cbranch_scc1 .LBB0_44
; __device__ __forceinline__ int otid(int wv) { int t; asm volatile("v_mbcnt_lo_u32_b32 %0, -1, 0\n\tv_mbcnt_hi_u32_b32 %0, -1, %0\n\tv_lshl_add_u32 %0, %1, 6, %0" : "=&v"(t) : "s"(wv)); return t; }
; __device__ __forceinline__ unsigned cvt_pk_bf16(float lo, float hi) { const f2_t v = {lo, hi}; const bf2_t b = __builtin_convertvector(v, bf2_t); return __builtin_bit_cast(unsigned, b); }
; __device__ __forceinline__ int upcol(int n) { return (n >> 8) * 128 + (n & 127) + ((n & 128) ? FFD : 0); }
; __device__ void convert_matrix(int wv, const float* src, int K, int N, int ld, int perm, bf16_t* dst, float* tileL, int rot) {
;     const int tid = otid(wv), G = gridDim.x, ntk = K >> 6, ntiles = ntk * (N >> 8);
;     for (int t = (blockIdx.x + G - (rot % G)) % G; t < ntiles; t += G) {
;         const int k0 = (t % ntk) * 64, n0 = (t / ntk) * 256;
;         f32x4 v[8];
; #pragma unroll
;         for (int ps = 0; ps < 8; ++ps) { const int idx = tid + ps * NTHR, kk = idx >> 6, n4 = (idx & 63) * 4; const int sc = perm ? upcol(n0 + n4) : n0 + n4;
;             v[ps] = *(const f32x4*)(src + (size_t)(k0 + kk) * ld + sc); }
; #pragma unroll
;         for (int ps = 0; ps < 8; ++ps) { const int idx = tid + ps * NTHR, kk = idx >> 6, n4 = (idx & 63) * 4;
;             float* tp = tileL + kk * 257 + n4; tp[0] = v[ps][0]; tp[1] = v[ps][1]; tp[2] = v[ps][2]; tp[3] = v[ps][3]; }
;         __syncthreads();
;         { const int n = tid >> 1, kh = (tid & 1) * 32;
; #pragma unroll
;             for (int q = 0; q < 4; ++q) { float e[8];
; #pragma unroll
;                 for (int j = 0; j < 8; ++j) e[j] = tileL[(kh + 8 * q + j) * 257 + n];
;                 u32x4 w; w.x = cvt_pk_bf16(e[0], e[1]); w.y = cvt_pk_bf16(e[2], e[3]); w.z = cvt_pk_bf16(e[4], e[5]); w.w = cvt_pk_bf16(e[6], e[7]);
;                 *(u32x4*)(dst + (size_t)(n0 + n) * K + k0 + kh + 8 * q) = w; } }
.LBB0_45:
	s_cmpk_gt_i32 s12, 0x5f
	v_mbcnt_lo_u32_b32 v2, -1, 0
	v_mbcnt_hi_u32_b32 v2, -1, v2
	v_lshl_add_u32 v2, s33, 6, v2
	s_cbranch_scc1 .LBB0_48
	v_add_u32_e32 v4, 0x200, v2
	v_ashrrev_i32_e32 v9, 6, v4
	v_add_u32_e32 v4, 0x400, v2
	v_ashrrev_i32_e32 v10, 6, v4
	v_add_u32_e32 v4, 0x600, v2
	v_ashrrev_i32_e32 v11, 6, v4
	v_add_u32_e32 v4, 0x800, v2
	v_lshlrev_b32_e32 v3, 2, v2
	v_ashrrev_i32_e32 v12, 6, v4
	v_add_u32_e32 v4, 0xa00, v2
	v_and_b32_e32 v6, 0xfc, v3
	v_ashrrev_i32_e32 v7, 1, v2
	v_lshlrev_b32_e32 v3, 5, v2
	v_ashrrev_i32_e32 v8, 6, v2
	v_ashrrev_i32_e32 v13, 6, v4
	v_add_u32_e32 v4, 0xc00, v2
	v_add_u32_e32 v2, 0xe00, v2
	v_and_b32_e32 v24, 32, v3
	s_movk_i32 s8, 0x404
	v_ashrrev_i32_e32 v14, 6, v4
	v_ashrrev_i32_e32 v15, 6, v2
	v_readlane_b32 s44, v253, 1
	s_add_u32 s4, s41, 0x17ec600
	v_lshl_add_u32 v23, v6, 2, 0
	v_lshl_add_u32 v25, v7, 2, 0
	v_mul_u32_u24_e32 v26, 0x412, v24
	v_mul_lo_u32 v2, v8, s8
	v_mul_lo_u32 v17, v9, s8
	v_mul_lo_u32 v18, v10, s8
	v_mul_lo_u32 v19, v11, s8
	v_mul_lo_u32 v20, v12, s8
	v_mul_lo_u32 v21, v13, s8
	v_mul_lo_u32 v22, v14, s8
	v_mul_lo_u32 v27, v15, s8
	v_readlane_b32 s52, v253, 9
	v_readlane_b32 s53, v253, 10
	s_addc_u32 s5, s42, 0
	v_mov_b32_e32 v3, 0
	s_lshl_b32 s10, s12, 6
	s_lshl_b32 s11, s34, 6
	s_movk_i32 s13, 0x1800
	v_mov_b64_e32 v[4:5], s[52:53]
	v_add_u32_e32 v16, v23, v2
	v_mad_u32_u24 v16, v8, 12, v16
	v_add_u32_e32 v17, v23, v17
	v_add_u32_e32 v18, v23, v18
	v_add_u32_e32 v19, v23, v19
	v_add_u32_e32 v20, v23, v20
	v_add_u32_e32 v21, v23, v21
	v_add_u32_e32 v22, v23, v22
	v_add_u32_e32 v23, v23, v27
	v_lshlrev_b32_e32 v2, 1, v24
	v_add_u32_e32 v24, v25, v26
	v_readlane_b32 s45, v253, 2
	v_readlane_b32 s46, v253, 3
	v_readlane_b32 s47, v253, 4
	v_readlane_b32 s48, v253, 5
	v_readlane_b32 s49, v253, 6
	v_readlane_b32 s50, v253, 7
	v_readlane_b32 s51, v253, 8
	v_readlane_b32 s54, v253, 11
	v_readlane_b32 s55, v253, 12
	v_readlane_b32 s56, v253, 13
	v_readlane_b32 s57, v253, 14
	v_readlane_b32 s58, v253, 15
	v_readlane_b32 s59, v253, 16
.LBB0_47:
	s_ashr_i32 s8, s12, 31
	s_lshr_b32 s8, s8, 28
	s_add_i32 s8, s12, s8
	s_ashr_i32 s8, s8, 4
	s_lshl_b32 s9, s8, 10
	s_lshl_b32 s16, s8, 8
	s_sub_i32 s8, s10, s9
	v_or_b32_e32 v26, s16, v6
	v_add_u32_e32 v25, s8, v8
	v_ashrrev_i32_e32 v27, 31, v26
	v_add_u32_e32 v30, s8, v9
	v_add_u32_e32 v32, s8, v10
	v_add_u32_e32 v34, s8, v11
	v_add_u32_e32 v36, s8, v12
	v_add_u32_e32 v38, s8, v13
	v_add_u32_e32 v40, s8, v14
	v_add_u32_e32 v42, s8, v15
	v_mad_i64_i32 v[28:29], s[14:15], v25, s13, v[4:5]
	v_lshlrev_b64 v[26:27], 2, v[26:27]
	v_mad_i64_i32 v[30:31], s[14:15], v30, s13, v[4:5]
	v_mad_i64_i32 v[32:33], s[14:15], v32, s13, v[4:5]
	v_mad_i64_i32 v[34:35], s[14:15], v34, s13, v[4:5]
	v_mad_i64_i32 v[36:37], s[14:15], v36, s13, v[4:5]
	v_mad_i64_i32 v[38:39], s[14:15], v38, s13, v[4:5]
	v_mad_i64_i32 v[40:41], s[14:15], v40, s13, v[4:5]
	v_mad_i64_i32 v[42:43], s[14:15], v42, s13, v[4:5]
	v_lshl_add_u64 v[28:29], v[28:29], 0, v[26:27]
	v_lshl_add_u64 v[30:31], v[30:31], 0, v[26:27]
	v_lshl_add_u64 v[44:45], v[32:33], 0, v[26:27]
	v_lshl_add_u64 v[46:47], v[34:35], 0, v[26:27]
	v_lshl_add_u64 v[48:49], v[36:37], 0, v[26:27]
	v_lshl_add_u64 v[50:51], v[38:39], 0, v[26:27]
	v_lshl_add_u64 v[52:53], v[40:41], 0, v[26:27]
	v_lshl_add_u64 v[54:55], v[42:43], 0, v[26:27]
	global_load_dwordx4 v[26:29], v[28:29], off
	s_nop 0
	global_load_dwordx4 v[30:33], v[30:31], off
	s_nop 0
	global_load_dwordx4 v[34:37], v[44:45], off
	global_load_dwordx4 v[38:41], v[46:47], off
	s_nop 0
	global_load_dwordx4 v[42:45], v[48:49], off
	s_nop 0
	global_load_dwordx4 v[46:49], v[50:51], off
	s_nop 0
	global_load_dwordx4 v[50:53], v[52:53], off
	s_nop 0
	global_load_dwordx4 v[54:57], v[54:55], off
	v_add_u32_e32 v58, s16, v7
	v_ashrrev_i32_e32 v59, 31, v58
	v_lshlrev_b64 v[58:59], 11, v[58:59]
	s_ashr_i32 s9, s8, 31
	v_lshl_add_u64 v[58:59], s[4:5], 0, v[58:59]
	s_add_i32 s12, s12, s34
	s_add_i32 s10, s10, s11
	v_lshl_add_u64 v[58:59], s[8:9], 1, v[58:59]
	s_cmpk_lt_i32 s12, 0x60
	v_lshl_add_u64 v[58:59], v[58:59], 0, v[2:3]
	s_waitcnt vmcnt(7)
	ds_write_b128 v16, v[26:29]
	s_waitcnt vmcnt(6)
	ds_write_b128 v16, v[30:33] offset:8320
	s_waitcnt vmcnt(5)
	ds_write_b128 v16, v[34:37] offset:16640
	s_waitcnt vmcnt(4)
	ds_write_b128 v16, v[38:41] offset:24960
	s_waitcnt vmcnt(3)
	ds_write_b128 v16, v[42:45] offset:33344
	s_waitcnt vmcnt(2)
	ds_write_b128 v16, v[46:49] offset:41664
	s_waitcnt vmcnt(1)
	ds_write_b128 v16, v[50:53] offset:49984
	s_waitcnt vmcnt(0)
	ds_write_b128 v16, v[54:57] offset:58304
	s_waitcnt lgkmcnt(0)
	s_barrier
	ds_read_b32 v25, v24
	ds_read_b32 v26, v24 offset:1040
	ds_read_b32 v27, v24 offset:2080
	ds_read_b32 v28, v24 offset:3120
	ds_read_b32 v29, v24 offset:4160
	ds_read_b32 v30, v24 offset:5200
	ds_read_b32 v31, v24 offset:6240
	ds_read_b32 v32, v24 offset:7280
	ds_read_b32 v33, v24 offset:8320
	ds_read_b32 v34, v24 offset:9360
	ds_read_b32 v35, v24 offset:10400
	ds_read_b32 v36, v24 offset:11440
	ds_read_b32 v37, v24 offset:12480
	ds_read_b32 v38, v24 offset:13520
	ds_read_b32 v39, v24 offset:14560
	ds_read_b32 v40, v24 offset:15600
	ds_read_b32 v41, v24 offset:16640
	ds_read_b32 v42, v24 offset:17680
	ds_read_b32 v43, v24 offset:18720
	ds_read_b32 v44, v24 offset:19760
	ds_read_b32 v45, v24 offset:20800
	ds_read_b32 v46, v24 offset:21840
	ds_read_b32 v47, v24 offset:22880
	ds_read_b32 v48, v24 offset:23920
	ds_read_b32 v49, v24 offset:24960
	ds_read_b32 v50, v24 offset:26000
	ds_read_b32 v51, v24 offset:27040
	ds_read_b32 v52, v24 offset:28080
	ds_read_b32 v53, v24 offset:29120
	ds_read_b32 v54, v24 offset:30160
	ds_read_b32 v55, v24 offset:31200
	ds_read_b32 v56, v24 offset:32240
	s_waitcnt lgkmcnt(14)
	v_cvt_pk_bf16_f32 v26, v25, v26
	v_cvt_pk_bf16_f32 v27, v27, v28
	v_cvt_pk_bf16_f32 v28, v29, v30
	v_cvt_pk_bf16_f32 v29, v31, v32
	v_cvt_pk_bf16_f32 v30, v33, v34
	v_cvt_pk_bf16_f32 v31, v35, v36
	v_cvt_pk_bf16_f32 v32, v37, v38
	v_cvt_pk_bf16_f32 v33, v39, v40
	v_cvt_pk_bf16_f32 v34, v41, v42
	s_waitcnt lgkmcnt(12)
	v_cvt_pk_bf16_f32 v35, v43, v44
	s_waitcnt lgkmcnt(10)
	v_cvt_pk_bf16_f32 v36, v45, v46
	s_waitcnt lgkmcnt(8)
	v_cvt_pk_bf16_f32 v37, v47, v48
	s_waitcnt lgkmcnt(6)
	v_cvt_pk_bf16_f32 v38, v49, v50
	s_waitcnt lgkmcnt(4)
	v_cvt_pk_bf16_f32 v39, v51, v52
	s_waitcnt lgkmcnt(2)
	v_cvt_pk_bf16_f32 v40, v53, v54
	s_waitcnt lgkmcnt(0)
	v_cvt_pk_bf16_f32 v41, v55, v56
	global_store_dwordx4 v[58:59], v[26:29], off
	global_store_dwordx4 v[58:59], v[30:33], off offset:16
	global_store_dwordx4 v[58:59], v[34:37], off offset:32
	global_store_dwordx4 v[58:59], v[38:41], off offset:48
	s_barrier
	s_cbranch_scc1 .LBB0_47
; __device__ __forceinline__ int otid(int wv) { int t; asm volatile("v_mbcnt_lo_u32_b32 %0, -1, 0\n\tv_mbcnt_hi_u32_b32 %0, -1, %0\n\tv_lshl_add_u32 %0, %1, 6, %0" : "=&v"(t) : "s"(wv)); return t; }
; __device__ __forceinline__ int upcol(int n) { return (n >> 8) * 128 + (n & 127) + ((n & 128) ? FFD : 0); }
; __device__ void convert_matrix(int wv, const float* src, int K, int N, int ld, int perm, bf16_t* dst, float* tileL, int rot) {
;     const int tid = otid(wv), G = gridDim.x, ntk = K >> 6, ntiles = ntk * (N >> 8);
;     for (int t = (blockIdx.x + G - (rot % G)) % G; t < ntiles; t += G) {
;         const int k0 = (t % ntk) * 64, n0 = (t / ntk) * 256;
;         f32x4 v[8];
; #pragma unroll
;         for (int ps = 0; ps < 8; ++ps) { const int idx = tid + ps * NTHR, kk = idx >> 6, n4 = (idx & 63) * 4; const int sc = perm ? upcol(n0 + n4) : n0 + n4;
;             v[ps] = *(const f32x4*)(src + (size_t)(k0 + kk) * ld + sc); }
; #pragma unroll
;         for (int ps = 0; ps < 8; ++ps) { const int idx = tid + ps * NTHR, kk = idx >> 6, n4 = (idx & 63) * 4;
;             float* tp = tileL + kk * 257 + n4; tp[0] = v[ps][0]; tp[1] = v[ps][1]; tp[2] = v[ps][2]; tp[3] = v[ps][3]; }
;         __syncthreads();
.LBB0_48:
	s_mul_hi_u32 s4, s40, 0xe0
	s_mul_i32 s4, s4, s39
	s_sub_i32 s4, 0xe0, s4
	s_sub_i32 s5, s4, s39
	s_cmp_ge_u32 s4, s39
	s_cselect_b32 s4, s5, s4
	s_sub_i32 s5, s4, s39
	s_cmp_ge_u32 s4, s39
	s_cselect_b32 s4, s5, s4
	s_sub_i32 s4, s3, s4
	s_mul_hi_u32 s5, s4, s38
	s_mul_i32 s5, s5, s34
	s_sub_i32 s4, s4, s5
	s_sub_i32 s5, s4, s34
	s_cmp_ge_u32 s4, s34
	s_cselect_b32 s4, s5, s4
	s_sub_i32 s5, s4, s34
	s_cmp_ge_u32 s4, s34
	s_cselect_b32 s10, s5, s4
	s_cmp_gt_i32 s10, 63
	v_mbcnt_lo_u32_b32 v2, -1, 0
	v_mbcnt_hi_u32_b32 v2, -1, v2
	v_lshl_add_u32 v2, s33, 6, v2
	s_cbranch_scc1 .LBB0_51
	v_lshlrev_b32_e32 v3, 2, v2
	v_and_b32_e32 v4, 0xfc, v3
	v_ashrrev_i32_e32 v5, 1, v2
	v_lshlrev_b32_e32 v3, 5, v2
	v_ashrrev_i32_e32 v6, 6, v2
	v_add_u32_e32 v7, 0x200, v2
	v_add_u32_e32 v8, 0x400, v2
	v_add_u32_e32 v9, 0x600, v2
	v_add_u32_e32 v10, 0x800, v2
	v_add_u32_e32 v11, 0xa00, v2
	v_add_u32_e32 v12, 0xc00, v2
	v_add_u32_e32 v2, 0xe00, v2
	v_and_b32_e32 v22, 32, v3
	s_movk_i32 s8, 0x404
	v_ashrrev_i32_e32 v7, 6, v7
	v_ashrrev_i32_e32 v8, 6, v8
	v_ashrrev_i32_e32 v9, 6, v9
	v_ashrrev_i32_e32 v10, 6, v10
	v_ashrrev_i32_e32 v11, 6, v11
	v_ashrrev_i32_e32 v12, 6, v12
	v_ashrrev_i32_e32 v13, 6, v2
	s_add_u32 s4, s41, 0x1aec600
	v_lshl_add_u32 v21, v4, 2, 0
	v_lshl_add_u32 v23, v5, 2, 0
	v_mul_u32_u24_e32 v24, 0x412, v22
	v_mul_lo_u32 v2, v6, s8
	v_mul_lo_u32 v15, v7, s8
	v_mul_lo_u32 v16, v8, s8
	v_mul_lo_u32 v17, v9, s8
	v_mul_lo_u32 v18, v10, s8
	v_mul_lo_u32 v19, v11, s8
	v_mul_lo_u32 v20, v12, s8
	v_mul_lo_u32 v25, v13, s8
	v_readlane_b32 s44, v253, 1
	s_addc_u32 s5, s42, 0
	v_mov_b32_e32 v3, 0
	s_lshl_b32 s11, s10, 6
	s_lshl_b32 s12, s34, 6
	v_add_u32_e32 v14, v21, v2
	v_mad_u32_u24 v14, v6, 12, v14
	v_add_u32_e32 v15, v21, v15
	v_add_u32_e32 v16, v21, v16
	v_add_u32_e32 v17, v21, v17
	v_add_u32_e32 v18, v21, v18
	v_add_u32_e32 v19, v21, v19
	v_add_u32_e32 v20, v21, v20
	v_add_u32_e32 v21, v21, v25
	v_lshlrev_b32_e32 v2, 1, v22
	v_add_u32_e32 v22, v23, v24
	v_readlane_b32 s56, v253, 13
	v_readlane_b32 s57, v253, 14
	v_readlane_b32 s45, v253, 2
	v_readlane_b32 s46, v253, 3
	v_readlane_b32 s47, v253, 4
	v_readlane_b32 s48, v253, 5
	v_readlane_b32 s49, v253, 6
	v_readlane_b32 s50, v253, 7
	v_readlane_b32 s51, v253, 8
	v_readlane_b32 s52, v253, 9
	v_readlane_b32 s53, v253, 10
	v_readlane_b32 s54, v253, 11
	v_readlane_b32 s55, v253, 12
	v_readlane_b32 s58, v253, 15
	v_readlane_b32 s59, v253, 16
.LBB0_50:
	s_ashr_i32 s8, s10, 31
	s_lshr_b32 s8, s8, 28
	s_add_i32 s8, s10, s8
	s_ashr_i32 s8, s8, 4
	s_lshl_b32 s13, s8, 10
	s_lshl_b32 s9, s8, 8
	s_sub_i32 s8, s11, s13
	v_add_u32_e32 v26, s8, v6
	v_add_u32_e32 v28, s8, v7
	v_add_u32_e32 v30, s8, v8
	v_add_u32_e32 v32, s8, v9
	v_add_u32_e32 v34, s8, v10
	v_add_u32_e32 v36, s8, v11
	v_add_u32_e32 v38, s8, v12
	v_add_u32_e32 v40, s8, v13
	v_or_b32_e32 v24, s9, v4
	v_ashrrev_i32_e32 v27, 31, v26
	v_ashrrev_i32_e32 v29, 31, v28
	v_ashrrev_i32_e32 v31, 31, v30
	v_ashrrev_i32_e32 v33, 31, v32
	v_ashrrev_i32_e32 v35, 31, v34
	v_ashrrev_i32_e32 v37, 31, v36
	v_ashrrev_i32_e32 v39, 31, v38
	v_ashrrev_i32_e32 v41, 31, v40
	v_ashrrev_i32_e32 v25, 31, v24
	v_lshlrev_b64 v[26:27], 12, v[26:27]
	v_lshlrev_b64 v[28:29], 12, v[28:29]
	v_lshlrev_b64 v[30:31], 12, v[30:31]
	v_lshlrev_b64 v[32:33], 12, v[32:33]
	v_lshlrev_b64 v[34:35], 12, v[34:35]
	v_lshlrev_b64 v[36:37], 12, v[36:37]
	v_lshlrev_b64 v[38:39], 12, v[38:39]
	v_lshlrev_b64 v[40:41], 12, v[40:41]
	v_lshlrev_b64 v[24:25], 2, v[24:25]
	v_lshl_add_u64 v[26:27], s[56:57], 0, v[26:27]
	v_lshl_add_u64 v[28:29], s[56:57], 0, v[28:29]
	v_lshl_add_u64 v[30:31], s[56:57], 0, v[30:31]
	v_lshl_add_u64 v[32:33], s[56:57], 0, v[32:33]
	v_lshl_add_u64 v[34:35], s[56:57], 0, v[34:35]
	v_lshl_add_u64 v[36:37], s[56:57], 0, v[36:37]
	v_lshl_add_u64 v[38:39], s[56:57], 0, v[38:39]
	v_lshl_add_u64 v[40:41], s[56:57], 0, v[40:41]
	v_lshl_add_u64 v[26:27], v[26:27], 0, v[24:25]
	v_lshl_add_u64 v[28:29], v[28:29], 0, v[24:25]
	v_lshl_add_u64 v[42:43], v[30:31], 0, v[24:25]
	v_lshl_add_u64 v[44:45], v[32:33], 0, v[24:25]
	v_lshl_add_u64 v[46:47], v[34:35], 0, v[24:25]
	v_lshl_add_u64 v[48:49], v[36:37], 0, v[24:25]
	v_lshl_add_u64 v[50:51], v[38:39], 0, v[24:25]
	v_lshl_add_u64 v[52:53], v[40:41], 0, v[24:25]
	global_load_dwordx4 v[24:27], v[26:27], off
	s_nop 0
	global_load_dwordx4 v[28:31], v[28:29], off
	s_nop 0
	global_load_dwordx4 v[32:35], v[42:43], off
	global_load_dwordx4 v[36:39], v[44:45], off
	s_nop 0
	global_load_dwordx4 v[40:43], v[46:47], off
	s_nop 0
	global_load_dwordx4 v[44:47], v[48:49], off
	s_nop 0
	global_load_dwordx4 v[48:51], v[50:51], off
	s_nop 0
	global_load_dwordx4 v[52:55], v[52:53], off
	v_add_u32_e32 v56, s9, v5
	v_ashrrev_i32_e32 v57, 31, v56
	v_lshlrev_b64 v[56:57], 11, v[56:57]
	s_ashr_i32 s9, s8, 31
	v_lshl_add_u64 v[56:57], s[4:5], 0, v[56:57]
	s_add_i32 s10, s10, s34
	s_add_i32 s11, s11, s12
	v_lshl_add_u64 v[56:57], s[8:9], 1, v[56:57]
	s_cmp_lt_i32 s10, 64
	v_lshl_add_u64 v[56:57], v[56:57], 0, v[2:3]
	s_waitcnt vmcnt(7)
	ds_write_b128 v14, v[24:27]
	s_waitcnt vmcnt(6)
	ds_write_b128 v14, v[28:31] offset:8320
	s_waitcnt vmcnt(5)
	ds_write_b128 v14, v[32:35] offset:16640
	s_waitcnt vmcnt(4)
	ds_write_b128 v14, v[36:39] offset:24960
	s_waitcnt vmcnt(3)
	ds_write_b128 v14, v[40:43] offset:33344
	s_waitcnt vmcnt(2)
	ds_write_b128 v14, v[44:47] offset:41664
	s_waitcnt vmcnt(1)
	ds_write_b128 v14, v[48:51] offset:49984
	s_waitcnt vmcnt(0)
	ds_write_b128 v14, v[52:55] offset:58304
	s_waitcnt lgkmcnt(0)
	s_barrier
; __device__ __forceinline__ int otid(int wv) { int t; asm volatile("v_mbcnt_lo_u32_b32 %0, -1, 0\n\tv_mbcnt_hi_u32_b32 %0, -1, %0\n\tv_lshl_add_u32 %0, %1, 6, %0" : "=&v"(t) : "s"(wv)); return t; }
; __device__ __forceinline__ unsigned cvt_pk_bf16(float lo, float hi) { const f2_t v = {lo, hi}; const bf2_t b = __builtin_convertvector(v, bf2_t); return __builtin_bit_cast(unsigned, b); }
; __device__ void convert_matrix(int wv, const float* src, int K, int N, int ld, int perm, bf16_t* dst, float* tileL, int rot) {
;     const int tid = otid(wv), G = gridDim.x, ntk = K >> 6, ntiles = ntk * (N >> 8);
;     for (int t = (blockIdx.x + G - (rot % G)) % G; t < ntiles; t += G) {
;         const int k0 = (t % ntk) * 64, n0 = (t / ntk) * 256;
;     ...
;         { const int n = tid >> 1, kh = (tid & 1) * 32;
; #pragma unroll
;             for (int q = 0; q < 4; ++q) { float e[8];
; #pragma unroll
;                 for (int j = 0; j < 8; ++j) e[j] = tileL[(kh + 8 * q + j) * 257 + n];
;                 u32x4 w; w.x = cvt_pk_bf16(e[0], e[1]); w.y = cvt_pk_bf16(e[2], e[3]); w.z = cvt_pk_bf16(e[4], e[5]); w.w = cvt_pk_bf16(e[6], e[7]);
;                 *(u32x4*)(dst + (size_t)(n0 + n) * K + k0 + kh + 8 * q) = w; } }
;         __syncthreads();
	ds_read_b32 v23, v22
	ds_read_b32 v24, v22 offset:1040
	ds_read_b32 v25, v22 offset:2080
	ds_read_b32 v26, v22 offset:3120
	ds_read_b32 v27, v22 offset:4160
	ds_read_b32 v28, v22 offset:5200
	ds_read_b32 v29, v22 offset:6240
	ds_read_b32 v30, v22 offset:7280
	ds_read_b32 v31, v22 offset:8320
	ds_read_b32 v32, v22 offset:9360
	ds_read_b32 v33, v22 offset:10400
	ds_read_b32 v34, v22 offset:11440
	ds_read_b32 v35, v22 offset:12480
	ds_read_b32 v36, v22 offset:13520
	ds_read_b32 v37, v22 offset:14560
	ds_read_b32 v38, v22 offset:15600
	ds_read_b32 v39, v22 offset:16640
	ds_read_b32 v40, v22 offset:17680
	ds_read_b32 v41, v22 offset:18720
	ds_read_b32 v42, v22 offset:19760
	ds_read_b32 v43, v22 offset:20800
	ds_read_b32 v44, v22 offset:21840
	ds_read_b32 v45, v22 offset:22880
	ds_read_b32 v46, v22 offset:23920
	ds_read_b32 v47, v22 offset:24960
	ds_read_b32 v48, v22 offset:26000
	ds_read_b32 v49, v22 offset:27040
	ds_read_b32 v50, v22 offset:28080
	ds_read_b32 v51, v22 offset:29120
	ds_read_b32 v52, v22 offset:30160
	ds_read_b32 v53, v22 offset:31200
	ds_read_b32 v54, v22 offset:32240
	s_waitcnt lgkmcnt(14)
	v_cvt_pk_bf16_f32 v24, v23, v24
	v_cvt_pk_bf16_f32 v25, v25, v26
	v_cvt_pk_bf16_f32 v26, v27, v28
	v_cvt_pk_bf16_f32 v27, v29, v30
	v_cvt_pk_bf16_f32 v28, v31, v32
	v_cvt_pk_bf16_f32 v29, v33, v34
	v_cvt_pk_bf16_f32 v30, v35, v36
	v_cvt_pk_bf16_f32 v31, v37, v38
	v_cvt_pk_bf16_f32 v32, v39, v40
	s_waitcnt lgkmcnt(12)
	v_cvt_pk_bf16_f32 v33, v41, v42
	s_waitcnt lgkmcnt(10)
	v_cvt_pk_bf16_f32 v34, v43, v44
	s_waitcnt lgkmcnt(8)
	v_cvt_pk_bf16_f32 v35, v45, v46
	s_waitcnt lgkmcnt(6)
	v_cvt_pk_bf16_f32 v36, v47, v48
	s_waitcnt lgkmcnt(4)
	v_cvt_pk_bf16_f32 v37, v49, v50
	s_waitcnt lgkmcnt(2)
	v_cvt_pk_bf16_f32 v38, v51, v52
	s_waitcnt lgkmcnt(0)
	v_cvt_pk_bf16_f32 v39, v53, v54
	global_store_dwordx4 v[56:57], v[24:27], off
	global_store_dwordx4 v[56:57], v[28:31], off offset:16
	global_store_dwordx4 v[56:57], v[32:35], off offset:32
	global_store_dwordx4 v[56:57], v[36:39], off offset:48
	s_barrier
	s_cbranch_scc1 .LBB0_50
.LBB0_51:
	s_lshr_b32 s4, s40, 27
	s_mul_i32 s4, s4, s39
	s_sub_i32 s4, 32, s4
	s_sub_i32 s5, s4, s39
	s_cmp_ge_u32 s4, s39
	s_cselect_b32 s4, s5, s4
	s_sub_i32 s5, s4, s39
	s_cmp_ge_u32 s4, s39
	s_cselect_b32 s4, s5, s4
	s_sub_i32 s4, s3, s4
	s_mul_hi_u32 s5, s4, s38
	s_mul_i32 s5, s5, s34
	s_sub_i32 s4, s4, s5
	s_sub_i32 s5, s4, s34
	s_cmp_ge_u32 s4, s34
	s_cselect_b32 s4, s5, s4
	s_sub_i32 s5, s4, s34
	s_cmp_ge_u32 s4, s34
	s_cselect_b32 s10, s5, s4
	s_cmp_gt_i32 s10, 63
	v_mbcnt_lo_u32_b32 v2, -1, 0
	v_mbcnt_hi_u32_b32 v2, -1, v2
	v_lshl_add_u32 v2, s33, 6, v2
	s_cbranch_scc1 .LBB0_54
	v_lshlrev_b32_e32 v3, 2, v2
	v_and_b32_e32 v4, 0xfc, v3
	v_ashrrev_i32_e32 v5, 1, v2
	v_lshlrev_b32_e32 v3, 5, v2
	v_ashrrev_i32_e32 v6, 6, v2
	v_add_u32_e32 v7, 0x200, v2
	v_add_u32_e32 v8, 0x400, v2
	v_add_u32_e32 v9, 0x600, v2
	v_add_u32_e32 v10, 0x800, v2
	v_add_u32_e32 v11, 0xa00, v2
	v_add_u32_e32 v12, 0xc00, v2
	v_add_u32_e32 v2, 0xe00, v2
	v_and_b32_e32 v22, 32, v3
	s_movk_i32 s8, 0x404
	v_ashrrev_i32_e32 v7, 6, v7
	v_ashrrev_i32_e32 v8, 6, v8
	v_ashrrev_i32_e32 v9, 6, v9
	v_ashrrev_i32_e32 v10, 6, v10
	v_ashrrev_i32_e32 v11, 6, v11
	v_ashrrev_i32_e32 v12, 6, v12
	v_ashrrev_i32_e32 v13, 6, v2
	s_add_u32 s4, s41, 0x1cec600
	v_lshl_add_u32 v21, v4, 2, 0
	v_lshl_add_u32 v23, v5, 2, 0
	v_mul_u32_u24_e32 v24, 0x412, v22
	v_mul_lo_u32 v2, v6, s8
	v_mul_lo_u32 v15, v7, s8
	v_mul_lo_u32 v16, v8, s8
	v_mul_lo_u32 v17, v9, s8
	v_mul_lo_u32 v18, v10, s8
	v_mul_lo_u32 v19, v11, s8
	v_mul_lo_u32 v20, v12, s8
	v_mul_lo_u32 v25, v13, s8
	v_readlane_b32 s44, v253, 1
	s_addc_u32 s5, s42, 0
	v_mov_b32_e32 v3, 0
	s_lshl_b32 s11, s10, 6
	s_lshl_b32 s12, s34, 6
	v_add_u32_e32 v14, v21, v2
	v_mad_u32_u24 v14, v6, 12, v14
	v_add_u32_e32 v15, v21, v15
	v_add_u32_e32 v16, v21, v16
	v_add_u32_e32 v17, v21, v17
	v_add_u32_e32 v18, v21, v18
	v_add_u32_e32 v19, v21, v19
	v_add_u32_e32 v20, v21, v20
	v_add_u32_e32 v21, v21, v25
	v_lshlrev_b32_e32 v2, 1, v22
	v_add_u32_e32 v22, v23, v24
	v_readlane_b32 s58, v253, 15
	v_readlane_b32 s59, v253, 16
	v_readlane_b32 s45, v253, 2
	v_readlane_b32 s46, v253, 3
	v_readlane_b32 s47, v253, 4
	v_readlane_b32 s48, v253, 5
	v_readlane_b32 s49, v253, 6
	v_readlane_b32 s50, v253, 7
	v_readlane_b32 s51, v253, 8
	v_readlane_b32 s52, v253, 9
	v_readlane_b32 s53, v253, 10
	v_readlane_b32 s54, v253, 11
	v_readlane_b32 s55, v253, 12
	v_readlane_b32 s56, v253, 13
	v_readlane_b32 s57, v253, 14
; __device__ __forceinline__ unsigned cvt_pk_bf16(float lo, float hi) { const f2_t v = {lo, hi}; const bf2_t b = __builtin_convertvector(v, bf2_t); return __builtin_bit_cast(unsigned, b); }
; __device__ __forceinline__ int upcol(int n) { return (n >> 8) * 128 + (n & 127) + ((n & 128) ? FFD : 0); }
; __device__ void convert_matrix(int wv, const float* src, int K, int N, int ld, int perm, bf16_t* dst, float* tileL, int rot) {
;     ...
;     for (int t = (blockIdx.x + G - (rot % G)) % G; t < ntiles; t += G) {
;         const int k0 = (t % ntk) * 64, n0 = (t / ntk) * 256;
;         f32x4 v[8];
; #pragma unroll
;         for (int ps = 0; ps < 8; ++ps) { const int idx = tid + ps * NTHR, kk = idx >> 6, n4 = (idx & 63) * 4; const int sc = perm ? upcol(n0 + n4) : n0 + n4;
;             v[ps] = *(const f32x4*)(src + (size_t)(k0 + kk) * ld + sc); }
; #pragma unroll
;         for (int ps = 0; ps < 8; ++ps) { const int idx = tid + ps * NTHR, kk = idx >> 6, n4 = (idx & 63) * 4;
;             float* tp = tileL + kk * 257 + n4; tp[0] = v[ps][0]; tp[1] = v[ps][1]; tp[2] = v[ps][2]; tp[3] = v[ps][3]; }
;         __syncthreads();
;         { const int n = tid >> 1, kh = (tid & 1) * 32;
; #pragma unroll
;             for (int q = 0; q < 4; ++q) { float e[8];
; #pragma unroll
;                 for (int j = 0; j < 8; ++j) e[j] = tileL[(kh + 8 * q + j) * 257 + n];
;                 u32x4 w; w.x = cvt_pk_bf16(e[0], e[1]); w.y = cvt_pk_bf16(e[2], e[3]); w.z = cvt_pk_bf16(e[4], e[5]); w.w = cvt_pk_bf16(e[6], e[7]);
;                 *(u32x4*)(dst + (size_t)(n0 + n) * K + k0 + kh + 8 * q) = w; } }
;         __syncthreads();
.LBB0_53:
	s_ashr_i32 s8, s10, 31
	s_lshr_b32 s8, s8, 28
	s_add_i32 s8, s10, s8
	s_ashr_i32 s8, s8, 4
	s_lshl_b32 s13, s8, 10
	s_lshl_b32 s9, s8, 8
	s_sub_i32 s8, s11, s13
	v_add_u32_e32 v26, s8, v6
	v_add_u32_e32 v28, s8, v7
	v_add_u32_e32 v30, s8, v8
	v_add_u32_e32 v32, s8, v9
	v_add_u32_e32 v34, s8, v10
	v_add_u32_e32 v36, s8, v11
	v_add_u32_e32 v38, s8, v12
	v_add_u32_e32 v40, s8, v13
	v_or_b32_e32 v24, s9, v4
	v_ashrrev_i32_e32 v27, 31, v26
	v_ashrrev_i32_e32 v29, 31, v28
	v_ashrrev_i32_e32 v31, 31, v30
	v_ashrrev_i32_e32 v33, 31, v32
	v_ashrrev_i32_e32 v35, 31, v34
	v_ashrrev_i32_e32 v37, 31, v36
	v_ashrrev_i32_e32 v39, 31, v38
	v_ashrrev_i32_e32 v41, 31, v40
	v_ashrrev_i32_e32 v25, 31, v24
	v_lshlrev_b64 v[26:27], 12, v[26:27]
	v_lshlrev_b64 v[28:29], 12, v[28:29]
	v_lshlrev_b64 v[30:31], 12, v[30:31]
	v_lshlrev_b64 v[32:33], 12, v[32:33]
	v_lshlrev_b64 v[34:35], 12, v[34:35]
	v_lshlrev_b64 v[36:37], 12, v[36:37]
	v_lshlrev_b64 v[38:39], 12, v[38:39]
	v_lshlrev_b64 v[40:41], 12, v[40:41]
	v_lshlrev_b64 v[24:25], 2, v[24:25]
	v_lshl_add_u64 v[26:27], s[58:59], 0, v[26:27]
	v_lshl_add_u64 v[28:29], s[58:59], 0, v[28:29]
	v_lshl_add_u64 v[30:31], s[58:59], 0, v[30:31]
	v_lshl_add_u64 v[32:33], s[58:59], 0, v[32:33]
	v_lshl_add_u64 v[34:35], s[58:59], 0, v[34:35]
	v_lshl_add_u64 v[36:37], s[58:59], 0, v[36:37]
	v_lshl_add_u64 v[38:39], s[58:59], 0, v[38:39]
	v_lshl_add_u64 v[40:41], s[58:59], 0, v[40:41]
	v_lshl_add_u64 v[26:27], v[26:27], 0, v[24:25]
	v_lshl_add_u64 v[28:29], v[28:29], 0, v[24:25]
	v_lshl_add_u64 v[42:43], v[30:31], 0, v[24:25]
	v_lshl_add_u64 v[44:45], v[32:33], 0, v[24:25]
	v_lshl_add_u64 v[46:47], v[34:35], 0, v[24:25]
	v_lshl_add_u64 v[48:49], v[36:37], 0, v[24:25]
	v_lshl_add_u64 v[50:51], v[38:39], 0, v[24:25]
	v_lshl_add_u64 v[52:53], v[40:41], 0, v[24:25]
	global_load_dwordx4 v[24:27], v[26:27], off
	s_nop 0
	global_load_dwordx4 v[28:31], v[28:29], off
	s_nop 0
	global_load_dwordx4 v[32:35], v[42:43], off
	global_load_dwordx4 v[36:39], v[44:45], off
	s_nop 0
	global_load_dwordx4 v[40:43], v[46:47], off
	s_nop 0
	global_load_dwordx4 v[44:47], v[48:49], off
	s_nop 0
	global_load_dwordx4 v[48:51], v[50:51], off
	s_nop 0
	global_load_dwordx4 v[52:55], v[52:53], off
	v_add_u32_e32 v56, s9, v5
	v_ashrrev_i32_e32 v57, 31, v56
	v_lshlrev_b64 v[56:57], 11, v[56:57]
	s_ashr_i32 s9, s8, 31
	v_lshl_add_u64 v[56:57], s[4:5], 0, v[56:57]
	s_add_i32 s10, s10, s34
	s_add_i32 s11, s11, s12
	v_lshl_add_u64 v[56:57], s[8:9], 1, v[56:57]
	s_cmp_lt_i32 s10, 64
	v_lshl_add_u64 v[56:57], v[56:57], 0, v[2:3]
	s_waitcnt vmcnt(7)
	ds_write_b128 v14, v[24:27]
	s_waitcnt vmcnt(6)
	ds_write_b128 v14, v[28:31] offset:8320
	s_waitcnt vmcnt(5)
	ds_write_b128 v14, v[32:35] offset:16640
	s_waitcnt vmcnt(4)
	ds_write_b128 v14, v[36:39] offset:24960
	s_waitcnt vmcnt(3)
	ds_write_b128 v14, v[40:43] offset:33344
	s_waitcnt vmcnt(2)
	ds_write_b128 v14, v[44:47] offset:41664
	s_waitcnt vmcnt(1)
	ds_write_b128 v14, v[48:51] offset:49984
	s_waitcnt vmcnt(0)
	ds_write_b128 v14, v[52:55] offset:58304
	s_waitcnt lgkmcnt(0)
	s_barrier
	ds_read_b32 v23, v22
	ds_read_b32 v24, v22 offset:1040
	ds_read_b32 v25, v22 offset:2080
	ds_read_b32 v26, v22 offset:3120
	ds_read_b32 v27, v22 offset:4160
	ds_read_b32 v28, v22 offset:5200
	ds_read_b32 v29, v22 offset:6240
	ds_read_b32 v30, v22 offset:7280
	ds_read_b32 v31, v22 offset:8320
	ds_read_b32 v32, v22 offset:9360
	ds_read_b32 v33, v22 offset:10400
	ds_read_b32 v34, v22 offset:11440
	ds_read_b32 v35, v22 offset:12480
	ds_read_b32 v36, v22 offset:13520
	ds_read_b32 v37, v22 offset:14560
	ds_read_b32 v38, v22 offset:15600
	ds_read_b32 v39, v22 offset:16640
	ds_read_b32 v40, v22 offset:17680
	ds_read_b32 v41, v22 offset:18720
	ds_read_b32 v42, v22 offset:19760
	ds_read_b32 v43, v22 offset:20800
	ds_read_b32 v44, v22 offset:21840
	ds_read_b32 v45, v22 offset:22880
	ds_read_b32 v46, v22 offset:23920
	ds_read_b32 v47, v22 offset:24960
	ds_read_b32 v48, v22 offset:26000
	ds_read_b32 v49, v22 offset:27040
	ds_read_b32 v50, v22 offset:28080
	ds_read_b32 v51, v22 offset:29120
	ds_read_b32 v52, v22 offset:30160
	ds_read_b32 v53, v22 offset:31200
	ds_read_b32 v54, v22 offset:32240
	s_waitcnt lgkmcnt(14)
	v_cvt_pk_bf16_f32 v24, v23, v24
	v_cvt_pk_bf16_f32 v25, v25, v26
	v_cvt_pk_bf16_f32 v26, v27, v28
	v_cvt_pk_bf16_f32 v27, v29, v30
	v_cvt_pk_bf16_f32 v28, v31, v32
	v_cvt_pk_bf16_f32 v29, v33, v34
	v_cvt_pk_bf16_f32 v30, v35, v36
	v_cvt_pk_bf16_f32 v31, v37, v38
	v_cvt_pk_bf16_f32 v32, v39, v40
	s_waitcnt lgkmcnt(12)
	v_cvt_pk_bf16_f32 v33, v41, v42
	s_waitcnt lgkmcnt(10)
	v_cvt_pk_bf16_f32 v34, v43, v44
	s_waitcnt lgkmcnt(8)
	v_cvt_pk_bf16_f32 v35, v45, v46
	s_waitcnt lgkmcnt(6)
	v_cvt_pk_bf16_f32 v36, v47, v48
	s_waitcnt lgkmcnt(4)
	v_cvt_pk_bf16_f32 v37, v49, v50
	s_waitcnt lgkmcnt(2)
	v_cvt_pk_bf16_f32 v38, v51, v52
	s_waitcnt lgkmcnt(0)
	v_cvt_pk_bf16_f32 v39, v53, v54
	global_store_dwordx4 v[56:57], v[24:27], off
	global_store_dwordx4 v[56:57], v[28:31], off offset:16
	global_store_dwordx4 v[56:57], v[32:35], off offset:32
	global_store_dwordx4 v[56:57], v[36:39], off offset:48
	s_barrier
	s_cbranch_scc1 .LBB0_53
; __device__ __forceinline__ int otid(int wv) { int t; asm volatile("v_mbcnt_lo_u32_b32 %0, -1, 0\n\tv_mbcnt_hi_u32_b32 %0, -1, %0\n\tv_lshl_add_u32 %0, %1, 6, %0" : "=&v"(t) : "s"(wv)); return t; }
; __device__ __forceinline__ unsigned cvt_pk_bf16(float lo, float hi) { const f2_t v = {lo, hi}; const bf2_t b = __builtin_convertvector(v, bf2_t); return __builtin_bit_cast(unsigned, b); }
; __device__ __forceinline__ int upcol(int n) { return (n >> 8) * 128 + (n & 127) + ((n & 128) ? FFD : 0); }
; __device__ void convert_matrix(int wv, const float* src, int K, int N, int ld, int perm, bf16_t* dst, float* tileL, int rot) {
;     const int tid = otid(wv), G = gridDim.x, ntk = K >> 6, ntiles = ntk * (N >> 8);
;     for (int t = (blockIdx.x + G - (rot % G)) % G; t < ntiles; t += G) {
;         const int k0 = (t % ntk) * 64, n0 = (t / ntk) * 256;
;         f32x4 v[8];
; #pragma unroll
;         for (int ps = 0; ps < 8; ++ps) { const int idx = tid + ps * NTHR, kk = idx >> 6, n4 = (idx & 63) * 4; const int sc = perm ? upcol(n0 + n4) : n0 + n4;
;             v[ps] = *(const f32x4*)(src + (size_t)(k0 + kk) * ld + sc); }
; #pragma unroll
;         for (int ps = 0; ps < 8; ++ps) { const int idx = tid + ps * NTHR, kk = idx >> 6, n4 = (idx & 63) * 4;
;             float* tp = tileL + kk * 257 + n4; tp[0] = v[ps][0]; tp[1] = v[ps][1]; tp[2] = v[ps][2]; tp[3] = v[ps][3]; }
;         __syncthreads();
;         { const int n = tid >> 1, kh = (tid & 1) * 32;
; #pragma unroll
;             for (int q = 0; q < 4; ++q) { float e[8];
; #pragma unroll
;                 for (int j = 0; j < 8; ++j) e[j] = tileL[(kh + 8 * q + j) * 257 + n];
;                 u32x4 w; w.x = cvt_pk_bf16(e[0], e[1]); w.y = cvt_pk_bf16(e[2], e[3]); w.z = cvt_pk_bf16(e[4], e[5]); w.w = cvt_pk_bf16(e[6], e[7]);
;                 *(u32x4*)(dst + (size_t)(n0 + n) * K + k0 + kh + 8 * q) = w; } }
;         __syncthreads();
.LBB0_54:
	s_mul_hi_u32 s4, s40, 0x60
	s_mul_i32 s4, s4, s39
	s_sub_i32 s4, 0x60, s4
	s_sub_i32 s5, s4, s39
	s_cmp_ge_u32 s4, s39
	s_cselect_b32 s4, s5, s4
	s_sub_i32 s5, s4, s39
	s_cmp_ge_u32 s4, s39
	s_cselect_b32 s4, s5, s4
	s_sub_i32 s4, s3, s4
	s_mul_hi_u32 s5, s4, s38
	s_mul_i32 s5, s5, s34
	s_sub_i32 s4, s4, s5
	s_sub_i32 s5, s4, s34
	s_cmp_ge_u32 s4, s34
	s_cselect_b32 s4, s5, s4
	s_sub_i32 s5, s4, s34
	s_cmp_ge_u32 s4, s34
	s_cselect_b32 s4, s5, s4
	v_writelane_b32 v253, s4, 34
	s_cmpk_gt_i32 s4, 0x15f
	v_mbcnt_lo_u32_b32 v2, -1, 0
	v_mbcnt_hi_u32_b32 v2, -1, v2
	v_lshl_add_u32 v2, s33, 6, v2
	s_cbranch_scc1 .LBB0_57
	v_lshlrev_b32_e32 v3, 2, v2
	v_and_b32_e32 v3, 0x7c, v3
	v_bfe_i32 v4, v2, 5, 1
	s_movk_i32 s8, 0xb00
	v_and_or_b32 v6, v4, s8, v3
	v_add_u32_e32 v4, 0x200, v2
	v_ashrrev_i32_e32 v9, 6, v4
	v_add_u32_e32 v4, 0x400, v2
	v_ashrrev_i32_e32 v10, 6, v4
	v_add_u32_e32 v4, 0x600, v2
	v_lshlrev_b32_e32 v3, 4, v2
	v_ashrrev_i32_e32 v11, 6, v4
	v_add_u32_e32 v4, 0x800, v2
	v_and_b32_e32 v3, 0x3f0, v3
	v_ashrrev_i32_e32 v12, 6, v4
	v_add_u32_e32 v4, 0xa00, v2
	v_add_u32_e32 v23, 0, v3
	v_ashrrev_i32_e32 v7, 1, v2
	v_lshlrev_b32_e32 v3, 5, v2
	v_ashrrev_i32_e32 v8, 6, v2
	v_ashrrev_i32_e32 v13, 6, v4
	v_add_u32_e32 v4, 0xc00, v2
	v_add_u32_e32 v2, 0xe00, v2
	v_and_b32_e32 v24, 32, v3
	s_movk_i32 s8, 0x404
	v_ashrrev_i32_e32 v14, 6, v4
	v_ashrrev_i32_e32 v15, 6, v2
	s_add_u32 s4, s41, 0x22ec600
	v_lshl_add_u32 v25, v7, 2, 0
	v_mul_u32_u24_e32 v26, 0x412, v24
	v_mul_lo_u32 v2, v8, s8
	v_mul_lo_u32 v17, v9, s8
	v_mul_lo_u32 v18, v10, s8
	v_mul_lo_u32 v19, v11, s8
	v_mul_lo_u32 v20, v12, s8
	v_mul_lo_u32 v21, v13, s8
	v_mul_lo_u32 v22, v14, s8
	v_mul_lo_u32 v27, v15, s8
	v_readlane_b32 s13, v253, 34
	s_addc_u32 s5, s42, 0
	v_mov_b32_e32 v3, 0
	s_lshl_b32 s10, s13, 6
	s_lshl_b32 s11, s34, 6
	s_movk_i32 s12, 0x5800
	v_mov_b64_e32 v[4:5], s[18:19]
	v_add_u32_e32 v16, v23, v2
	v_mad_u32_u24 v16, v8, 12, v16
	v_add_u32_e32 v17, v23, v17
	v_add_u32_e32 v18, v23, v18
	v_add_u32_e32 v19, v23, v19
	v_add_u32_e32 v20, v23, v20
	v_add_u32_e32 v21, v23, v21
	v_add_u32_e32 v22, v23, v22
	v_add_u32_e32 v23, v23, v27
	v_lshlrev_b32_e32 v2, 1, v24
	v_add_u32_e32 v24, v25, v26
.LBB0_56:
	s_ashr_i32 s8, s13, 31
	s_lshr_b32 s8, s8, 28
	s_add_i32 s8, s13, s8
	s_ashr_i32 s9, s8, 4
	s_lshl_b32 s8, s9, 10
	v_lshl_add_u32 v26, s9, 7, v6
	s_sub_i32 s8, s10, s8
	v_ashrrev_i32_e32 v27, 31, v26
	v_add_u32_e32 v25, s8, v8
	v_add_u32_e32 v30, s8, v9
	v_add_u32_e32 v32, s8, v10
	v_add_u32_e32 v34, s8, v11
	v_add_u32_e32 v36, s8, v12
	v_add_u32_e32 v38, s8, v13
	v_add_u32_e32 v40, s8, v14
	v_add_u32_e32 v42, s8, v15
	v_lshlrev_b64 v[26:27], 2, v[26:27]
	v_mad_i64_i32 v[28:29], s[14:15], v25, s12, v[4:5]
	v_mad_i64_i32 v[30:31], s[14:15], v30, s12, v[4:5]
	v_mad_i64_i32 v[32:33], s[14:15], v32, s12, v[4:5]
	v_mad_i64_i32 v[34:35], s[14:15], v34, s12, v[4:5]
	v_mad_i64_i32 v[36:37], s[14:15], v36, s12, v[4:5]
	v_mad_i64_i32 v[38:39], s[14:15], v38, s12, v[4:5]
	v_mad_i64_i32 v[40:41], s[14:15], v40, s12, v[4:5]
	v_mad_i64_i32 v[42:43], s[14:15], v42, s12, v[4:5]
	v_lshl_add_u64 v[28:29], v[28:29], 0, v[26:27]
	v_lshl_add_u64 v[30:31], v[30:31], 0, v[26:27]
	v_lshl_add_u64 v[44:45], v[32:33], 0, v[26:27]
	v_lshl_add_u64 v[46:47], v[34:35], 0, v[26:27]
	v_lshl_add_u64 v[48:49], v[36:37], 0, v[26:27]
	v_lshl_add_u64 v[50:51], v[38:39], 0, v[26:27]
	v_lshl_add_u64 v[52:53], v[40:41], 0, v[26:27]
	v_lshl_add_u64 v[54:55], v[42:43], 0, v[26:27]
	global_load_dwordx4 v[26:29], v[28:29], off
	s_nop 0
	global_load_dwordx4 v[30:33], v[30:31], off
	s_nop 0
	global_load_dwordx4 v[34:37], v[44:45], off
	global_load_dwordx4 v[38:41], v[46:47], off
	s_nop 0
	global_load_dwordx4 v[42:45], v[48:49], off
	s_nop 0
	global_load_dwordx4 v[46:49], v[50:51], off
	s_nop 0
	global_load_dwordx4 v[50:53], v[52:53], off
	s_nop 0
	global_load_dwordx4 v[54:57], v[54:55], off
	v_lshl_add_u32 v58, s9, 8, v7
	v_ashrrev_i32_e32 v59, 31, v58
	v_lshlrev_b64 v[58:59], 11, v[58:59]
	s_ashr_i32 s9, s8, 31
	v_lshl_add_u64 v[58:59], s[4:5], 0, v[58:59]
	s_add_i32 s13, s13, s34
	s_add_i32 s10, s10, s11
	v_lshl_add_u64 v[58:59], s[8:9], 1, v[58:59]
	s_cmpk_lt_i32 s13, 0x160
	v_lshl_add_u64 v[58:59], v[58:59], 0, v[2:3]
	s_waitcnt vmcnt(7)
	ds_write_b128 v16, v[26:29]
	s_waitcnt vmcnt(6)
	ds_write_b128 v16, v[30:33] offset:8320
	s_waitcnt vmcnt(5)
	ds_write_b128 v16, v[34:37] offset:16640
	s_waitcnt vmcnt(4)
	ds_write_b128 v16, v[38:41] offset:24960
	s_waitcnt vmcnt(3)
	ds_write_b128 v16, v[42:45] offset:33344
	s_waitcnt vmcnt(2)
	ds_write_b128 v16, v[46:49] offset:41664
	s_waitcnt vmcnt(1)
	ds_write_b128 v16, v[50:53] offset:49984
	s_waitcnt vmcnt(0)
	ds_write_b128 v16, v[54:57] offset:58304
	s_waitcnt lgkmcnt(0)
	s_barrier
	ds_read_b32 v25, v24
	ds_read_b32 v26, v24 offset:1040
	ds_read_b32 v27, v24 offset:2080
	ds_read_b32 v28, v24 offset:3120
	ds_read_b32 v29, v24 offset:4160
	ds_read_b32 v30, v24 offset:5200
	ds_read_b32 v31, v24 offset:6240
	ds_read_b32 v32, v24 offset:7280
	ds_read_b32 v33, v24 offset:8320
	ds_read_b32 v34, v24 offset:9360
	ds_read_b32 v35, v24 offset:10400
	ds_read_b32 v36, v24 offset:11440
	ds_read_b32 v37, v24 offset:12480
	ds_read_b32 v38, v24 offset:13520
	ds_read_b32 v39, v24 offset:14560
	ds_read_b32 v40, v24 offset:15600
	ds_read_b32 v41, v24 offset:16640
	ds_read_b32 v42, v24 offset:17680
	ds_read_b32 v43, v24 offset:18720
	ds_read_b32 v44, v24 offset:19760
	ds_read_b32 v45, v24 offset:20800
	ds_read_b32 v46, v24 offset:21840
	ds_read_b32 v47, v24 offset:22880
	ds_read_b32 v48, v24 offset:23920
	ds_read_b32 v49, v24 offset:24960
	ds_read_b32 v50, v24 offset:26000
	ds_read_b32 v51, v24 offset:27040
	ds_read_b32 v52, v24 offset:28080
	ds_read_b32 v53, v24 offset:29120
	ds_read_b32 v54, v24 offset:30160
	ds_read_b32 v55, v24 offset:31200
	ds_read_b32 v56, v24 offset:32240
	s_waitcnt lgkmcnt(14)
	v_cvt_pk_bf16_f32 v26, v25, v26
	v_cvt_pk_bf16_f32 v27, v27, v28
	v_cvt_pk_bf16_f32 v28, v29, v30
	v_cvt_pk_bf16_f32 v29, v31, v32
	v_cvt_pk_bf16_f32 v30, v33, v34
	v_cvt_pk_bf16_f32 v31, v35, v36
	v_cvt_pk_bf16_f32 v32, v37, v38
	v_cvt_pk_bf16_f32 v33, v39, v40
	v_cvt_pk_bf16_f32 v34, v41, v42
	s_waitcnt lgkmcnt(12)
	v_cvt_pk_bf16_f32 v35, v43, v44
	s_waitcnt lgkmcnt(10)
	v_cvt_pk_bf16_f32 v36, v45, v46
	s_waitcnt lgkmcnt(8)
	v_cvt_pk_bf16_f32 v37, v47, v48
	s_waitcnt lgkmcnt(6)
	v_cvt_pk_bf16_f32 v38, v49, v50
	s_waitcnt lgkmcnt(4)
	v_cvt_pk_bf16_f32 v39, v51, v52
	s_waitcnt lgkmcnt(2)
	v_cvt_pk_bf16_f32 v40, v53, v54
	s_waitcnt lgkmcnt(0)
	v_cvt_pk_bf16_f32 v41, v55, v56
	global_store_dwordx4 v[58:59], v[26:29], off
	global_store_dwordx4 v[58:59], v[30:33], off offset:16
	global_store_dwordx4 v[58:59], v[34:37], off offset:32
	global_store_dwordx4 v[58:59], v[38:41], off offset:48
	s_barrier
	s_cbranch_scc1 .LBB0_56
; __device__ __forceinline__ int otid(int wv) { int t; asm volatile("v_mbcnt_lo_u32_b32 %0, -1, 0\n\tv_mbcnt_hi_u32_b32 %0, -1, %0\n\tv_lshl_add_u32 %0, %1, 6, %0" : "=&v"(t) : "s"(wv)); return t; }
; __device__ __forceinline__ int upcol(int n) { return (n >> 8) * 128 + (n & 127) + ((n & 128) ? FFD : 0); }
; __device__ void convert_matrix(int wv, const float* src, int K, int N, int ld, int perm, bf16_t* dst, float* tileL, int rot) {
;     const int tid = otid(wv), G = gridDim.x, ntk = K >> 6, ntiles = ntk * (N >> 8);
;     for (int t = (blockIdx.x + G - (rot % G)) % G; t < ntiles; t += G) {
;         const int k0 = (t % ntk) * 64, n0 = (t / ntk) * 256;
;         f32x4 v[8];
; #pragma unroll
;         for (int ps = 0; ps < 8; ++ps) { const int idx = tid + ps * NTHR, kk = idx >> 6, n4 = (idx & 63) * 4; const int sc = perm ? upcol(n0 + n4) : n0 + n4;
;             v[ps] = *(const f32x4*)(src + (size_t)(k0 + kk) * ld + sc); }
; #pragma unroll
;         for (int ps = 0; ps < 8; ++ps) { const int idx = tid + ps * NTHR, kk = idx >> 6, n4 = (idx & 63) * 4;
;             float* tp = tileL + kk * 257 + n4; tp[0] = v[ps][0]; tp[1] = v[ps][1]; tp[2] = v[ps][2]; tp[3] = v[ps][3]; }
;         __syncthreads();
;         { const int n = tid >> 1, kh = (tid & 1) * 32;
.LBB0_57:
	s_mul_hi_u32 s4, s40, 0xc0
	s_mul_i32 s4, s4, s39
	s_sub_i32 s4, 0xc0, s4
	s_sub_i32 s5, s4, s39
	s_cmp_ge_u32 s4, s39
	s_cselect_b32 s4, s5, s4
	s_sub_i32 s5, s4, s39
	s_cmp_ge_u32 s4, s39
	s_cselect_b32 s4, s5, s4
	s_sub_i32 s4, s3, s4
	s_mul_hi_u32 s5, s4, s38
	s_mul_i32 s5, s5, s34
	s_sub_i32 s4, s4, s5
	s_sub_i32 s5, s4, s34
	s_cmp_ge_u32 s4, s34
	s_cselect_b32 s4, s5, s4
	s_sub_i32 s5, s4, s34
	s_cmp_ge_u32 s4, s34
	s_cselect_b32 s8, s5, s4
	s_cmpk_gt_i32 s8, 0xaf
	v_mbcnt_lo_u32_b32 v2, -1, 0
	v_mbcnt_hi_u32_b32 v2, -1, v2
	v_lshl_add_u32 v2, s33, 6, v2
	s_cbranch_scc1 .LBB0_60
	v_add_u32_e32 v5, 0x200, v2
	v_ashrrev_i32_e32 v9, 6, v5
	v_add_u32_e32 v5, 0x400, v2
	v_ashrrev_i32_e32 v10, 6, v5
	v_add_u32_e32 v5, 0x600, v2
	v_ashrrev_i32_e32 v11, 6, v5
	v_add_u32_e32 v5, 0x800, v2
	v_lshlrev_b32_e32 v3, 2, v2
	v_ashrrev_i32_e32 v12, 6, v5
	v_add_u32_e32 v5, 0xa00, v2
	v_and_b32_e32 v6, 0xfc, v3
	v_ashrrev_i32_e32 v7, 1, v2
	v_lshlrev_b32_e32 v3, 5, v2
	v_ashrrev_i32_e32 v8, 6, v2
	v_ashrrev_i32_e32 v13, 6, v5
	v_add_u32_e32 v5, 0xc00, v2
	v_add_u32_e32 v2, 0xe00, v2
	s_add_u32 s4, s41, 0x38ec600
	v_and_b32_e32 v24, 32, v3
	s_movk_i32 s9, 0x404
	v_ashrrev_i32_e32 v14, 6, v5
	v_ashrrev_i32_e32 v15, 6, v2
	s_addc_u32 s5, s42, 0
	v_lshl_add_u32 v4, v6, 2, 0
	v_lshl_add_u32 v25, v7, 2, 0
	v_mul_u32_u24_e32 v26, 0x412, v24
	v_mul_lo_u32 v2, v8, s9
	v_mul_lo_u32 v5, v9, s9
	v_mul_lo_u32 v18, v10, s9
	v_mul_lo_u32 v19, v11, s9
	v_mul_lo_u32 v20, v12, s9
	v_mul_lo_u32 v21, v13, s9
	v_mul_lo_u32 v22, v14, s9
	v_mul_lo_u32 v23, v15, s9
	v_mov_b32_e32 v3, 0
	s_lshl_b32 s9, s8, 6
	s_lshl_b32 s10, s34, 6
	v_add_u32_e32 v16, v4, v2
	v_mad_u32_u24 v16, v8, 12, v16
	v_add_u32_e32 v17, v4, v5
	v_add_u32_e32 v18, v4, v18
	v_add_u32_e32 v19, v4, v19
	v_add_u32_e32 v20, v4, v20
	v_add_u32_e32 v21, v4, v21
	v_add_u32_e32 v22, v4, v22
	v_add_u32_e32 v23, v4, v23
	s_movk_i32 s11, 0x1600
	v_mov_b64_e32 v[4:5], s[4:5]
	v_lshlrev_b32_e32 v2, 1, v24
	v_add_u32_e32 v24, v25, v26
; __device__ __forceinline__ unsigned cvt_pk_bf16(float lo, float hi) { const f2_t v = {lo, hi}; const bf2_t b = __builtin_convertvector(v, bf2_t); return __builtin_bit_cast(unsigned, b); }
; __device__ __forceinline__ int upcol(int n) { return (n >> 8) * 128 + (n & 127) + ((n & 128) ? FFD : 0); }
; __device__ void convert_matrix(int wv, const float* src, int K, int N, int ld, int perm, bf16_t* dst, float* tileL, int rot) {
;     ...
;     for (int t = (blockIdx.x + G - (rot % G)) % G; t < ntiles; t += G) {
;         const int k0 = (t % ntk) * 64, n0 = (t / ntk) * 256;
;         f32x4 v[8];
; #pragma unroll
;         for (int ps = 0; ps < 8; ++ps) { const int idx = tid + ps * NTHR, kk = idx >> 6, n4 = (idx & 63) * 4; const int sc = perm ? upcol(n0 + n4) : n0 + n4;
;             v[ps] = *(const f32x4*)(src + (size_t)(k0 + kk) * ld + sc); }
; #pragma unroll
;         for (int ps = 0; ps < 8; ++ps) { const int idx = tid + ps * NTHR, kk = idx >> 6, n4 = (idx & 63) * 4;
;             float* tp = tileL + kk * 257 + n4; tp[0] = v[ps][0]; tp[1] = v[ps][1]; tp[2] = v[ps][2]; tp[3] = v[ps][3]; }
;         __syncthreads();
;         { const int n = tid >> 1, kh = (tid & 1) * 32;
; #pragma unroll
;             for (int q = 0; q < 4; ++q) { float e[8];
; #pragma unroll
;                 for (int j = 0; j < 8; ++j) e[j] = tileL[(kh + 8 * q + j) * 257 + n];
;                 u32x4 w; w.x = cvt_pk_bf16(e[0], e[1]); w.y = cvt_pk_bf16(e[2], e[3]); w.z = cvt_pk_bf16(e[4], e[5]); w.w = cvt_pk_bf16(e[6], e[7]);
;                 *(u32x4*)(dst + (size_t)(n0 + n) * K + k0 + kh + 8 * q) = w; } }
;         __syncthreads();
.LBB0_59:
	s_mul_hi_i32 s4, s8, 0x2e8ba2e9
	s_lshr_b32 s5, s4, 31
	s_ashr_i32 s4, s4, 3
	s_add_i32 s4, s4, s5
	s_mul_i32 s12, s4, 0xfffff500
	s_lshl_b32 s5, s4, 8
	s_add_i32 s4, s9, s12
	v_add_u32_e32 v28, s4, v8
	v_add_u32_e32 v30, s4, v9
	v_add_u32_e32 v32, s4, v10
	v_add_u32_e32 v34, s4, v11
	v_add_u32_e32 v36, s4, v12
	v_add_u32_e32 v38, s4, v13
	v_add_u32_e32 v40, s4, v14
	v_add_u32_e32 v42, s4, v15
	v_or_b32_e32 v26, s5, v6
	v_ashrrev_i32_e32 v29, 31, v28
	v_ashrrev_i32_e32 v31, 31, v30
	v_ashrrev_i32_e32 v33, 31, v32
	v_ashrrev_i32_e32 v35, 31, v34
	v_ashrrev_i32_e32 v37, 31, v36
	v_ashrrev_i32_e32 v39, 31, v38
	v_ashrrev_i32_e32 v41, 31, v40
	v_ashrrev_i32_e32 v43, 31, v42
	v_ashrrev_i32_e32 v27, 31, v26
	v_lshlrev_b64 v[28:29], 12, v[28:29]
	v_lshlrev_b64 v[30:31], 12, v[30:31]
	v_lshlrev_b64 v[32:33], 12, v[32:33]
	v_lshlrev_b64 v[34:35], 12, v[34:35]
	v_lshlrev_b64 v[36:37], 12, v[36:37]
	v_lshlrev_b64 v[38:39], 12, v[38:39]
	v_lshlrev_b64 v[40:41], 12, v[40:41]
	v_lshlrev_b64 v[42:43], 12, v[42:43]
	v_lshlrev_b64 v[26:27], 2, v[26:27]
	v_lshl_add_u64 v[28:29], s[24:25], 0, v[28:29]
	v_lshl_add_u64 v[30:31], s[24:25], 0, v[30:31]
	v_lshl_add_u64 v[32:33], s[24:25], 0, v[32:33]
	v_lshl_add_u64 v[34:35], s[24:25], 0, v[34:35]
	v_lshl_add_u64 v[36:37], s[24:25], 0, v[36:37]
	v_lshl_add_u64 v[38:39], s[24:25], 0, v[38:39]
	v_lshl_add_u64 v[40:41], s[24:25], 0, v[40:41]
	v_lshl_add_u64 v[42:43], s[24:25], 0, v[42:43]
	v_lshl_add_u64 v[28:29], v[28:29], 0, v[26:27]
	v_lshl_add_u64 v[30:31], v[30:31], 0, v[26:27]
	v_lshl_add_u64 v[44:45], v[32:33], 0, v[26:27]
	v_lshl_add_u64 v[46:47], v[34:35], 0, v[26:27]
	v_lshl_add_u64 v[48:49], v[36:37], 0, v[26:27]
	v_lshl_add_u64 v[50:51], v[38:39], 0, v[26:27]
	v_lshl_add_u64 v[52:53], v[40:41], 0, v[26:27]
	v_lshl_add_u64 v[54:55], v[42:43], 0, v[26:27]
	global_load_dwordx4 v[26:29], v[28:29], off
	s_nop 0
	global_load_dwordx4 v[30:33], v[30:31], off
	s_nop 0
	global_load_dwordx4 v[34:37], v[44:45], off
	global_load_dwordx4 v[38:41], v[46:47], off
	s_nop 0
	global_load_dwordx4 v[42:45], v[48:49], off
	s_nop 0
	global_load_dwordx4 v[46:49], v[50:51], off
	s_nop 0
	global_load_dwordx4 v[50:53], v[52:53], off
	s_nop 0
	global_load_dwordx4 v[54:57], v[54:55], off
	v_add_u32_e32 v25, s5, v7
	v_mad_i64_i32 v[58:59], s[12:13], v25, s11, v[4:5]
	s_ashr_i32 s5, s4, 31
	s_add_i32 s8, s8, s34
	s_add_i32 s9, s9, s10
	v_lshl_add_u64 v[58:59], s[4:5], 1, v[58:59]
	s_cmpk_lt_i32 s8, 0xb0
	v_lshl_add_u64 v[58:59], v[58:59], 0, v[2:3]
	s_waitcnt vmcnt(7)
	ds_write_b128 v16, v[26:29]
	s_waitcnt vmcnt(6)
	ds_write_b128 v16, v[30:33] offset:8320
	s_waitcnt vmcnt(5)
	ds_write_b128 v16, v[34:37] offset:16640
	s_waitcnt vmcnt(4)
	ds_write_b128 v16, v[38:41] offset:24960
	s_waitcnt vmcnt(3)
	ds_write_b128 v16, v[42:45] offset:33344
	s_waitcnt vmcnt(2)
	ds_write_b128 v16, v[46:49] offset:41664
	s_waitcnt vmcnt(1)
	ds_write_b128 v16, v[50:53] offset:49984
	s_waitcnt vmcnt(0)
	ds_write_b128 v16, v[54:57] offset:58304
	s_waitcnt lgkmcnt(0)
	s_barrier
	ds_read_b32 v25, v24
	ds_read_b32 v26, v24 offset:1040
	ds_read_b32 v27, v24 offset:2080
	ds_read_b32 v28, v24 offset:3120
	ds_read_b32 v29, v24 offset:4160
	ds_read_b32 v30, v24 offset:5200
	ds_read_b32 v31, v24 offset:6240
	ds_read_b32 v32, v24 offset:7280
	ds_read_b32 v33, v24 offset:8320
	ds_read_b32 v34, v24 offset:9360
	ds_read_b32 v35, v24 offset:10400
	ds_read_b32 v36, v24 offset:11440
	ds_read_b32 v37, v24 offset:12480
	ds_read_b32 v38, v24 offset:13520
	ds_read_b32 v39, v24 offset:14560
	ds_read_b32 v40, v24 offset:15600
	ds_read_b32 v41, v24 offset:16640
	ds_read_b32 v42, v24 offset:17680
	ds_read_b32 v43, v24 offset:18720
	ds_read_b32 v44, v24 offset:19760
	ds_read_b32 v45, v24 offset:20800
	ds_read_b32 v46, v24 offset:21840
	ds_read_b32 v47, v24 offset:22880
	ds_read_b32 v48, v24 offset:23920
	ds_read_b32 v49, v24 offset:24960
	ds_read_b32 v50, v24 offset:26000
	ds_read_b32 v51, v24 offset:27040
	ds_read_b32 v52, v24 offset:28080
	ds_read_b32 v53, v24 offset:29120
	ds_read_b32 v54, v24 offset:30160
	ds_read_b32 v55, v24 offset:31200
	ds_read_b32 v56, v24 offset:32240
	s_waitcnt lgkmcnt(14)
	v_cvt_pk_bf16_f32 v26, v25, v26
	v_cvt_pk_bf16_f32 v27, v27, v28
	v_cvt_pk_bf16_f32 v28, v29, v30
	v_cvt_pk_bf16_f32 v29, v31, v32
	v_cvt_pk_bf16_f32 v30, v33, v34
	v_cvt_pk_bf16_f32 v31, v35, v36
	v_cvt_pk_bf16_f32 v32, v37, v38
	v_cvt_pk_bf16_f32 v33, v39, v40
	v_cvt_pk_bf16_f32 v34, v41, v42
	s_waitcnt lgkmcnt(12)
	v_cvt_pk_bf16_f32 v35, v43, v44
	s_waitcnt lgkmcnt(10)
	v_cvt_pk_bf16_f32 v36, v45, v46
	s_waitcnt lgkmcnt(8)
	v_cvt_pk_bf16_f32 v37, v47, v48
	s_waitcnt lgkmcnt(6)
	v_cvt_pk_bf16_f32 v38, v49, v50
	s_waitcnt lgkmcnt(4)
	v_cvt_pk_bf16_f32 v39, v51, v52
	s_waitcnt lgkmcnt(2)
	v_cvt_pk_bf16_f32 v40, v53, v54
	s_waitcnt lgkmcnt(0)
	v_cvt_pk_bf16_f32 v41, v55, v56
	global_store_dwordx4 v[58:59], v[26:29], off
	global_store_dwordx4 v[58:59], v[30:33], off offset:16
	global_store_dwordx4 v[58:59], v[34:37], off offset:32
	global_store_dwordx4 v[58:59], v[38:41], off offset:48
	s_barrier
	s_cbranch_scc1 .LBB0_59

; __device__ __forceinline__ int otid(int wv) { int t; asm volatile("v_mbcnt_lo_u32_b32 %0, -1, 0\n\tv_mbcnt_hi_u32_b32 %0, -1, %0\n\tv_lshl_add_u32 %0, %1, 6, %0" : "=&v"(t) : "s"(wv)); return t; }
; __device__ __forceinline__ int upcol(int n) { return (n >> 8) * 128 + (n & 127) + ((n & 128) ? FFD : 0); }
; __device__ void convert_matrix(int wv, const float* src, int K, int N, int ld, int perm, bf16_t* dst, float* tileL, int rot) {
;     const int tid = otid(wv), G = gridDim.x, ntk = K >> 6, ntiles = ntk * (N >> 8);
;     for (int t = (blockIdx.x + G - (rot % G)) % G; t < ntiles; t += G) {
;         const int k0 = (t % ntk) * 64, n0 = (t / ntk) * 256;
;         f32x4 v[8];
; #pragma unroll
;         for (int ps = 0; ps < 8; ++ps) { const int idx = tid + ps * NTHR, kk = idx >> 6, n4 = (idx & 63) * 4; const int sc = perm ? upcol(n0 + n4) : n0 + n4;
;             v[ps] = *(const f32x4*)(src + (size_t)(k0 + kk) * ld + sc); }
; #pragma unroll
;         for (int ps = 0; ps < 8; ++ps) { const int idx = tid + ps * NTHR, kk = idx >> 6, n4 = (idx & 63) * 4;
;             float* tp = tileL + kk * 257 + n4; tp[0] = v[ps][0]; tp[1] = v[ps][1]; tp[2] = v[ps][2]; tp[3] = v[ps][3]; }
;         __syncthreads();
;         { const int n = tid >> 1, kh = (tid & 1) * 32;
.LBB0_116:
	s_or_b64 exec, exec, s[0:1]
	s_mul_hi_u32 s0, s40, 48
	s_mul_i32 s0, s0, s39
	s_sub_i32 s0, 48, s0
	s_sub_i32 s1, s0, s39
	s_cmp_ge_u32 s0, s39
	s_cselect_b32 s0, s1, s0
	s_sub_i32 s1, s0, s39
	s_cmp_ge_u32 s0, s39
	s_cselect_b32 s0, s1, s0
	s_sub_i32 s0, s3, s0
	s_mul_hi_u32 s1, s0, s38
	s_mul_i32 s1, s1, s34
	s_sub_i32 s0, s0, s1
	s_sub_i32 s1, s0, s34
	s_cmp_ge_u32 s0, s34
	s_cselect_b32 s0, s1, s0
	s_sub_i32 s1, s0, s34
	s_cmp_ge_u32 s0, s34
	s_cselect_b32 s3, s1, s0
	s_cmpk_gt_i32 s3, 0x7f
	v_mbcnt_lo_u32_b32 v0, -1, 0
	v_mbcnt_hi_u32_b32 v0, -1, v0
	v_lshl_add_u32 v0, s33, 6, v0
	s_cbranch_scc1 .LBB0_119
	v_lshlrev_b32_e32 v1, 2, v0
	s_add_u32 s0, s41, 0x3ec600
	v_and_b32_e32 v2, 0xfc, v1
	v_ashrrev_i32_e32 v3, 1, v0
	v_lshlrev_b32_e32 v1, 5, v0
	v_ashrrev_i32_e32 v4, 6, v0
	v_add_u32_e32 v5, 0x200, v0
	v_add_u32_e32 v6, 0x400, v0
	v_add_u32_e32 v7, 0x600, v0
	v_add_u32_e32 v8, 0x800, v0
	v_add_u32_e32 v9, 0xa00, v0
	v_add_u32_e32 v10, 0xc00, v0
	v_add_u32_e32 v0, 0xe00, v0
	s_addc_u32 s1, s42, 0
	v_and_b32_e32 v20, 32, v1
	s_movk_i32 s10, 0x404
	v_ashrrev_i32_e32 v5, 6, v5
	v_ashrrev_i32_e32 v6, 6, v6
	v_ashrrev_i32_e32 v7, 6, v7
	v_ashrrev_i32_e32 v8, 6, v8
	v_ashrrev_i32_e32 v9, 6, v9
	v_ashrrev_i32_e32 v10, 6, v10
	v_ashrrev_i32_e32 v11, 6, v0
	s_add_u32 s8, s41, 0x1eec600
	v_lshl_add_u32 v19, v2, 2, 0
	v_lshl_add_u32 v21, v3, 2, 0
	v_mul_u32_u24_e32 v23, 0x412, v20
	v_mul_lo_u32 v0, v4, s10
	v_mul_lo_u32 v13, v5, s10
	v_mul_lo_u32 v14, v6, s10
	v_mul_lo_u32 v15, v7, s10
	v_mul_lo_u32 v16, v8, s10
	v_mul_lo_u32 v17, v9, s10
	v_mul_lo_u32 v18, v10, s10
	v_mul_lo_u32 v24, v11, s10
	s_addc_u32 s9, s42, 0
	v_mov_b32_e32 v1, 0
	s_lshl_b32 s12, s3, 6
	s_lshl_b32 s13, s34, 6
	v_add_u32_e32 v12, v19, v0
	v_mad_u32_u24 v12, v4, 12, v12
	v_add_u32_e32 v13, v19, v13
	v_add_u32_e32 v14, v19, v14
	v_add_u32_e32 v15, v19, v15
	v_add_u32_e32 v16, v19, v16
	v_add_u32_e32 v17, v19, v17
	v_add_u32_e32 v18, v19, v18
	v_add_u32_e32 v19, v19, v24
	v_lshlrev_b32_e32 v0, 1, v20
	v_add_u32_e32 v20, v21, v23
; __device__ __forceinline__ unsigned cvt_pk_bf16(float lo, float hi) { const f2_t v = {lo, hi}; const bf2_t b = __builtin_convertvector(v, bf2_t); return __builtin_bit_cast(unsigned, b); }
; __device__ __forceinline__ int upcol(int n) { return (n >> 8) * 128 + (n & 127) + ((n & 128) ? FFD : 0); }
; __device__ void convert_matrix(int wv, const float* src, int K, int N, int ld, int perm, bf16_t* dst, float* tileL, int rot) {
;     ...
;     for (int t = (blockIdx.x + G - (rot % G)) % G; t < ntiles; t += G) {
;         const int k0 = (t % ntk) * 64, n0 = (t / ntk) * 256;
;         f32x4 v[8];
; #pragma unroll
;         for (int ps = 0; ps < 8; ++ps) { const int idx = tid + ps * NTHR, kk = idx >> 6, n4 = (idx & 63) * 4; const int sc = perm ? upcol(n0 + n4) : n0 + n4;
;             v[ps] = *(const f32x4*)(src + (size_t)(k0 + kk) * ld + sc); }
; #pragma unroll
;         for (int ps = 0; ps < 8; ++ps) { const int idx = tid + ps * NTHR, kk = idx >> 6, n4 = (idx & 63) * 4;
;             float* tp = tileL + kk * 257 + n4; tp[0] = v[ps][0]; tp[1] = v[ps][1]; tp[2] = v[ps][2]; tp[3] = v[ps][3]; }
;         __syncthreads();
;         { const int n = tid >> 1, kh = (tid & 1) * 32;
; #pragma unroll
;             for (int q = 0; q < 4; ++q) { float e[8];
; #pragma unroll
;                 for (int j = 0; j < 8; ++j) e[j] = tileL[(kh + 8 * q + j) * 257 + n];
;                 u32x4 w; w.x = cvt_pk_bf16(e[0], e[1]); w.y = cvt_pk_bf16(e[2], e[3]); w.z = cvt_pk_bf16(e[4], e[5]); w.w = cvt_pk_bf16(e[6], e[7]);
;                 *(u32x4*)(dst + (size_t)(n0 + n) * K + k0 + kh + 8 * q) = w; } }
;         __syncthreads();
.LBB0_118:
	s_ashr_i32 s10, s3, 31
	s_lshr_b32 s10, s10, 27
	s_add_i32 s10, s3, s10
	s_ashr_i32 s10, s10, 5
	s_lshl_b32 s14, s10, 11
	s_lshl_b32 s11, s10, 8
	s_sub_i32 s10, s12, s14
	v_add_u32_e32 v26, s10, v4
	v_or_b32_e32 v24, s11, v2
	v_add_u32_e32 v28, s10, v5
	v_add_u32_e32 v30, s10, v6
	v_add_u32_e32 v32, s10, v7
	v_add_u32_e32 v34, s10, v8
	v_add_u32_e32 v36, s10, v9
	v_add_u32_e32 v38, s10, v10
	v_add_u32_e32 v40, s10, v11
	v_ashrrev_i32_e32 v27, 31, v26
	v_ashrrev_i32_e32 v25, 31, v24
	v_ashrrev_i32_e32 v29, 31, v28
	v_ashrrev_i32_e32 v31, 31, v30
	v_ashrrev_i32_e32 v33, 31, v32
	v_ashrrev_i32_e32 v35, 31, v34
	v_ashrrev_i32_e32 v37, 31, v36
	v_ashrrev_i32_e32 v39, 31, v38
	v_ashrrev_i32_e32 v41, 31, v40
	v_lshlrev_b64 v[26:27], 12, v[26:27]
	v_lshlrev_b64 v[24:25], 2, v[24:25]
	v_lshlrev_b64 v[28:29], 12, v[28:29]
	v_lshlrev_b64 v[30:31], 12, v[30:31]
	v_lshlrev_b64 v[32:33], 12, v[32:33]
	v_lshlrev_b64 v[34:35], 12, v[34:35]
	v_lshlrev_b64 v[36:37], 12, v[36:37]
	v_lshlrev_b64 v[38:39], 12, v[38:39]
	v_lshlrev_b64 v[40:41], 12, v[40:41]
	v_lshl_add_u64 v[26:27], s[0:1], 0, v[26:27]
	v_lshl_add_u64 v[28:29], s[0:1], 0, v[28:29]
	v_lshl_add_u64 v[30:31], s[0:1], 0, v[30:31]
	v_lshl_add_u64 v[32:33], s[0:1], 0, v[32:33]
	v_lshl_add_u64 v[34:35], s[0:1], 0, v[34:35]
	v_lshl_add_u64 v[36:37], s[0:1], 0, v[36:37]
	v_lshl_add_u64 v[38:39], s[0:1], 0, v[38:39]
	v_lshl_add_u64 v[40:41], s[0:1], 0, v[40:41]
	v_lshl_add_u64 v[56:57], v[26:27], 0, v[24:25]
	v_lshl_add_u64 v[58:59], v[28:29], 0, v[24:25]
	v_lshl_add_u64 v[60:61], v[30:31], 0, v[24:25]
	v_lshl_add_u64 v[62:63], v[32:33], 0, v[24:25]
	v_lshl_add_u64 v[64:65], v[34:35], 0, v[24:25]
	v_lshl_add_u64 v[66:67], v[36:37], 0, v[24:25]
	v_lshl_add_u64 v[68:69], v[38:39], 0, v[24:25]
	v_lshl_add_u64 v[70:71], v[40:41], 0, v[24:25]
	global_load_dwordx4 v[24:27], v[56:57], off
	global_load_dwordx4 v[28:31], v[58:59], off
	global_load_dwordx4 v[32:35], v[60:61], off
	global_load_dwordx4 v[36:39], v[62:63], off
	global_load_dwordx4 v[40:43], v[64:65], off
	global_load_dwordx4 v[44:47], v[66:67], off
	global_load_dwordx4 v[48:51], v[68:69], off
	global_load_dwordx4 v[52:55], v[70:71], off
	v_add_u32_e32 v56, s11, v3
	v_ashrrev_i32_e32 v57, 31, v56
	v_lshlrev_b64 v[56:57], 12, v[56:57]
	s_ashr_i32 s11, s10, 31
	v_lshl_add_u64 v[56:57], s[8:9], 0, v[56:57]
	s_add_i32 s3, s3, s34
	s_add_i32 s12, s12, s13
	v_lshl_add_u64 v[56:57], s[10:11], 1, v[56:57]
	s_cmpk_lt_i32 s3, 0x80
	v_lshl_add_u64 v[56:57], v[56:57], 0, v[0:1]
	s_waitcnt vmcnt(7)
	ds_write_b128 v12, v[24:27]
	s_waitcnt vmcnt(6)
	ds_write_b128 v12, v[28:31] offset:8320
	s_waitcnt vmcnt(5)
	ds_write_b128 v12, v[32:35] offset:16640
	s_waitcnt vmcnt(4)
	ds_write_b128 v12, v[36:39] offset:24960
	s_waitcnt vmcnt(3)
	ds_write_b128 v12, v[40:43] offset:33344
	s_waitcnt vmcnt(2)
	ds_write_b128 v12, v[44:47] offset:41664
	s_waitcnt vmcnt(1)
	ds_write_b128 v12, v[48:51] offset:49984
	s_waitcnt vmcnt(0)
	ds_write_b128 v12, v[52:55] offset:58304
	s_waitcnt lgkmcnt(0)
	s_barrier
	ds_read_b32 v21, v20
	ds_read_b32 v23, v20 offset:1040
	ds_read_b32 v25, v20 offset:2080
	ds_read_b32 v26, v20 offset:3120
	ds_read_b32 v27, v20 offset:4160
	ds_read_b32 v28, v20 offset:5200
	ds_read_b32 v29, v20 offset:6240
	ds_read_b32 v30, v20 offset:7280
	ds_read_b32 v31, v20 offset:8320
	ds_read_b32 v32, v20 offset:9360
	ds_read_b32 v33, v20 offset:10400
	ds_read_b32 v34, v20 offset:11440
	ds_read_b32 v35, v20 offset:12480
	ds_read_b32 v36, v20 offset:13520
	ds_read_b32 v37, v20 offset:14560
	ds_read_b32 v38, v20 offset:15600
	ds_read_b32 v39, v20 offset:16640
	ds_read_b32 v40, v20 offset:17680
	ds_read_b32 v41, v20 offset:18720
	ds_read_b32 v42, v20 offset:19760
	ds_read_b32 v43, v20 offset:20800
	ds_read_b32 v44, v20 offset:21840
	ds_read_b32 v45, v20 offset:22880
	ds_read_b32 v46, v20 offset:23920
	ds_read_b32 v47, v20 offset:24960
	ds_read_b32 v48, v20 offset:26000
	ds_read_b32 v49, v20 offset:27040
	ds_read_b32 v50, v20 offset:28080
	ds_read_b32 v51, v20 offset:29120
	ds_read_b32 v52, v20 offset:30160
	ds_read_b32 v53, v20 offset:31200
	ds_read_b32 v54, v20 offset:32240
	s_waitcnt lgkmcnt(14)
	v_cvt_pk_bf16_f32 v24, v21, v23
	v_cvt_pk_bf16_f32 v25, v25, v26
	v_cvt_pk_bf16_f32 v26, v27, v28
	v_cvt_pk_bf16_f32 v27, v29, v30
	v_cvt_pk_bf16_f32 v28, v31, v32
	v_cvt_pk_bf16_f32 v29, v33, v34
	v_cvt_pk_bf16_f32 v30, v35, v36
	v_cvt_pk_bf16_f32 v31, v37, v38
	v_cvt_pk_bf16_f32 v32, v39, v40
	s_waitcnt lgkmcnt(12)
	v_cvt_pk_bf16_f32 v33, v41, v42
	s_waitcnt lgkmcnt(10)
	v_cvt_pk_bf16_f32 v34, v43, v44
	s_waitcnt lgkmcnt(8)
	v_cvt_pk_bf16_f32 v35, v45, v46
	s_waitcnt lgkmcnt(6)
	v_cvt_pk_bf16_f32 v36, v47, v48
	s_waitcnt lgkmcnt(4)
	v_cvt_pk_bf16_f32 v37, v49, v50
	s_waitcnt lgkmcnt(2)
	v_cvt_pk_bf16_f32 v38, v51, v52
	s_waitcnt lgkmcnt(0)
	v_cvt_pk_bf16_f32 v39, v53, v54
	global_store_dwordx4 v[56:57], v[24:27], off
	global_store_dwordx4 v[56:57], v[28:31], off offset:16
	global_store_dwordx4 v[56:57], v[32:35], off offset:32
	global_store_dwordx4 v[56:57], v[36:39], off offset:48
	s_barrier
	s_cbranch_scc1 .LBB0_118

; __device__ __forceinline__ int otid(int wv) { int t; asm volatile("v_mbcnt_lo_u32_b32 %0, -1, 0\n\tv_mbcnt_hi_u32_b32 %0, -1, %0\n\tv_lshl_add_u32 %0, %1, 6, %0" : "=&v"(t) : "s"(wv)); return t; }
; __device__ __forceinline__ unsigned cvt_pk_bf16(float lo, float hi) { const f2_t v = {lo, hi}; const bf2_t b = __builtin_convertvector(v, bf2_t); return __builtin_bit_cast(unsigned, b); }
; __device__ __forceinline__ int upcol(int n) { return (n >> 8) * 128 + (n & 127) + ((n & 128) ? FFD : 0); }
; __device__ void convert_matrix(int wv, const float* src, int K, int N, int ld, int perm, bf16_t* dst, float* tileL, int rot) {
;     const int tid = otid(wv), G = gridDim.x, ntk = K >> 6, ntiles = ntk * (N >> 8);
;     for (int t = (blockIdx.x + G - (rot % G)) % G; t < ntiles; t += G) {
;         const int k0 = (t % ntk) * 64, n0 = (t / ntk) * 256;
;         f32x4 v[8];
; #pragma unroll
;         for (int ps = 0; ps < 8; ++ps) { const int idx = tid + ps * NTHR, kk = idx >> 6, n4 = (idx & 63) * 4; const int sc = perm ? upcol(n0 + n4) : n0 + n4;
;             v[ps] = *(const f32x4*)(src + (size_t)(k0 + kk) * ld + sc); }
; #pragma unroll
;         for (int ps = 0; ps < 8; ++ps) { const int idx = tid + ps * NTHR, kk = idx >> 6, n4 = (idx & 63) * 4;
;             float* tp = tileL + kk * 257 + n4; tp[0] = v[ps][0]; tp[1] = v[ps][1]; tp[2] = v[ps][2]; tp[3] = v[ps][3]; }
;         __syncthreads();
;         { const int n = tid >> 1, kh = (tid & 1) * 32;
; #pragma unroll
;             for (int q = 0; q < 4; ++q) { float e[8];
; #pragma unroll
;                 for (int j = 0; j < 8; ++j) e[j] = tileL[(kh + 8 * q + j) * 257 + n];
;                 u32x4 w; w.x = cvt_pk_bf16(e[0], e[1]); w.y = cvt_pk_bf16(e[2], e[3]); w.z = cvt_pk_bf16(e[4], e[5]); w.w = cvt_pk_bf16(e[6], e[7]);
;                 *(u32x4*)(dst + (size_t)(n0 + n) * K + k0 + kh + 8 * q) = w; } }
;         __syncthreads();
; __global__ void __launch_bounds__(NTHR, 2) mega(Params p) {
;     ...
;             convert_matrix(wv, p.f_w_up + (size_t)(i + 1) * 1024 * NUP, 1024, NUP, NUP, 1, wup + (size_t)((i + 1) & 1) * NUP * 1024, ldsf, 0);
.LBB0_277:
	s_or_b64 exec, exec, s[4:5]
	v_readlane_b32 s4, v255, 22
	s_add_u32 s65, s4, 0x22ec600
	v_readlane_b32 s5, v255, 23
	s_addc_u32 s68, s5, 0
	s_add_u32 s41, s4, 0x38ec600
	s_addc_u32 s64, s5, 0
	s_andn2_b64 vcc, exec, s[6:7]
	s_waitcnt lgkmcnt(0)
	s_barrier
	s_cbranch_vccnz .LBB0_284
	v_readlane_b32 s4, v255, 21
	s_add_i32 s15, s4, 1
	v_readlane_b32 s4, v254, 5
	v_readlane_b32 s5, v254, 6
	s_and_b32 s14, s15, 1
	s_andn2_b64 vcc, exec, s[4:5]
	s_movk_i32 s21, 0x5800
	v_mbcnt_lo_u32_b32 v2, -1, 0
	v_mbcnt_hi_u32_b32 v2, -1, v2
	v_lshl_add_u32 v2, s33, 6, v2
	s_cbranch_vccnz .LBB0_281
	v_lshlrev_b32_e32 v1, 2, v2
	s_mul_i32 s4, s15, 0x1600000
	v_and_b32_e32 v1, 0x7c, v1
	v_bfe_i32 v3, v2, 5, 1
	s_movk_i32 s10, 0xb00
	v_lshlrev_b32_e32 v5, 5, v2
	s_mul_hi_u32 s5, s15, 0x1600000
	s_add_u32 s4, s18, s4
	v_and_or_b32 v1, v3, s10, v1
	v_lshlrev_b32_e32 v3, 4, v2
	v_ashrrev_i32_e32 v4, 1, v2
	v_and_b32_e32 v22, 32, v5
	v_ashrrev_i32_e32 v5, 6, v2
	v_add_u32_e32 v6, 0x200, v2
	v_add_u32_e32 v7, 0x400, v2
	v_add_u32_e32 v8, 0x600, v2
	v_add_u32_e32 v9, 0x800, v2
	v_add_u32_e32 v10, 0xa00, v2
	v_add_u32_e32 v11, 0xc00, v2
	v_add_u32_e32 v2, 0xe00, v2
	s_addc_u32 s5, s19, s5
	s_mul_i32 s6, s14, 0xb00000
	v_and_b32_e32 v3, 0x3f0, v3
	v_ashrrev_i32_e32 v6, 6, v6
	v_ashrrev_i32_e32 v7, 6, v7
	v_ashrrev_i32_e32 v8, 6, v8
	v_ashrrev_i32_e32 v9, 6, v9
	v_ashrrev_i32_e32 v10, 6, v10
	v_ashrrev_i32_e32 v11, 6, v11
	v_ashrrev_i32_e32 v12, 6, v2
	s_movk_i32 s10, 0x404
	s_add_u32 s6, s65, s6
	v_add_u32_e32 v3, 0, v3
	v_lshl_add_u32 v21, v4, 2, 0
	v_mul_u32_u24_e32 v23, 0x412, v22
	v_mul_lo_u32 v2, v5, s10
	v_mul_lo_u32 v14, v6, s10
	v_mul_lo_u32 v15, v7, s10
	v_mul_lo_u32 v16, v8, s10
	v_mul_lo_u32 v17, v9, s10
	v_mul_lo_u32 v18, v10, s10
	v_mul_lo_u32 v19, v11, s10
	v_mul_lo_u32 v20, v12, s10
	v_readlane_b32 s20, v253, 33
	s_addc_u32 s7, s68, 0
	s_lshl_b32 s16, s20, 6
	s_lshl_b32 s17, s34, 6
	v_add_u32_e32 v13, v3, v2
	v_mad_u32_u24 v13, v5, 12, v13
	v_add_u32_e32 v14, v3, v14
	v_add_u32_e32 v15, v3, v15
	v_add_u32_e32 v16, v3, v16
	v_add_u32_e32 v17, v3, v17
	v_add_u32_e32 v18, v3, v18
	v_add_u32_e32 v19, v3, v19
	v_add_u32_e32 v20, v3, v20
	v_lshlrev_b32_e32 v2, 1, v22
	v_add_u32_e32 v21, v21, v23
.LBB0_280:
	s_ashr_i32 s10, s20, 31
	s_lshr_b32 s10, s10, 28
	s_add_i32 s10, s20, s10
	s_ashr_i32 s11, s10, 4
	s_lshl_b32 s10, s11, 10
	s_sub_i32 s10, s16, s10
	v_lshl_add_u32 v22, s11, 7, v1
	v_add_u32_e32 v3, s10, v5
	v_mov_b64_e32 v[50:51], s[4:5]
	v_ashrrev_i32_e32 v23, 31, v22
	v_mad_i64_i32 v[24:25], s[22:23], v3, s21, v[50:51]
	v_lshlrev_b64 v[52:53], 2, v[22:23]
	v_lshl_add_u64 v[22:23], v[24:25], 0, v[52:53]
	v_add_u32_e32 v3, s10, v6
	global_load_dwordx4 v[22:25], v[22:23], off
	v_mad_i64_i32 v[26:27], s[22:23], v3, s21, v[50:51]
	v_lshl_add_u64 v[26:27], v[26:27], 0, v[52:53]
	v_add_u32_e32 v3, s10, v7
	global_load_dwordx4 v[26:29], v[26:27], off
	v_mad_i64_i32 v[30:31], s[22:23], v3, s21, v[50:51]
	v_lshl_add_u64 v[30:31], v[30:31], 0, v[52:53]
	v_add_u32_e32 v3, s10, v8
	global_load_dwordx4 v[30:33], v[30:31], off
	v_mad_i64_i32 v[34:35], s[22:23], v3, s21, v[50:51]
	v_lshl_add_u64 v[34:35], v[34:35], 0, v[52:53]
	v_add_u32_e32 v3, s10, v9
	global_load_dwordx4 v[34:37], v[34:35], off
	v_mad_i64_i32 v[38:39], s[22:23], v3, s21, v[50:51]
	v_lshl_add_u64 v[38:39], v[38:39], 0, v[52:53]
	v_add_u32_e32 v3, s10, v10
	global_load_dwordx4 v[38:41], v[38:39], off
	v_mad_i64_i32 v[42:43], s[22:23], v3, s21, v[50:51]
	v_lshl_add_u64 v[42:43], v[42:43], 0, v[52:53]
	v_add_u32_e32 v3, s10, v11
	global_load_dwordx4 v[42:45], v[42:43], off
	v_mad_i64_i32 v[46:47], s[22:23], v3, s21, v[50:51]
	v_lshl_add_u64 v[46:47], v[46:47], 0, v[52:53]
	v_add_u32_e32 v3, s10, v12
	global_load_dwordx4 v[46:49], v[46:47], off
	v_mad_i64_i32 v[50:51], s[22:23], v3, s21, v[50:51]
	v_lshl_add_u64 v[50:51], v[50:51], 0, v[52:53]
	global_load_dwordx4 v[50:53], v[50:51], off
	v_mov_b32_e32 v3, v0
	s_add_i32 s20, s20, s34
	s_add_i32 s16, s16, s17
	s_waitcnt vmcnt(7)
	ds_write_b128 v13, v[22:25]
	s_waitcnt vmcnt(6)
	ds_write_b128 v13, v[26:29] offset:8320
	s_waitcnt vmcnt(5)
	ds_write_b128 v13, v[30:33] offset:16640
	s_waitcnt vmcnt(4)
	ds_write_b128 v13, v[34:37] offset:24960
	s_waitcnt vmcnt(3)
	ds_write_b128 v13, v[38:41] offset:33344
	s_waitcnt vmcnt(2)
	ds_write_b128 v13, v[42:45] offset:41664
	s_waitcnt vmcnt(1)
	ds_write_b128 v13, v[46:49] offset:49984
	s_waitcnt vmcnt(0)
	ds_write_b128 v13, v[50:53] offset:58304
	v_lshl_add_u32 v22, s11, 8, v4
	v_ashrrev_i32_e32 v23, 31, v22
	v_lshlrev_b64 v[22:23], 11, v[22:23]
	v_lshl_add_u64 v[22:23], s[6:7], 0, v[22:23]
	s_ashr_i32 s11, s10, 31
	v_lshl_add_u64 v[22:23], s[10:11], 1, v[22:23]
	s_waitcnt lgkmcnt(0)
	s_barrier
	v_lshl_add_u64 v[26:27], v[22:23], 0, v[2:3]
	ds_read_b32 v3, v21
	ds_read_b32 v22, v21 offset:1040
	ds_read_b32 v23, v21 offset:2080
	ds_read_b32 v24, v21 offset:3120
	ds_read_b32 v25, v21 offset:4160
	ds_read_b32 v28, v21 offset:5200
	ds_read_b32 v29, v21 offset:6240
	ds_read_b32 v30, v21 offset:7280
	s_waitcnt lgkmcnt(6)
	v_cvt_pk_bf16_f32 v22, v3, v22
	s_waitcnt lgkmcnt(4)
	v_cvt_pk_bf16_f32 v23, v23, v24
	s_waitcnt lgkmcnt(2)
	v_cvt_pk_bf16_f32 v24, v25, v28
	s_cmpk_lt_i32 s20, 0x160
	s_waitcnt lgkmcnt(0)
	v_cvt_pk_bf16_f32 v25, v29, v30
	global_store_dwordx4 v[26:27], v[22:25], off
	ds_read_b32 v3, v21 offset:8320
	ds_read_b32 v22, v21 offset:9360
	ds_read_b32 v23, v21 offset:10400
	ds_read_b32 v24, v21 offset:11440
	ds_read_b32 v25, v21 offset:12480
	ds_read_b32 v28, v21 offset:13520
	ds_read_b32 v29, v21 offset:14560
	ds_read_b32 v30, v21 offset:15600
	s_waitcnt lgkmcnt(6)
	v_cvt_pk_bf16_f32 v22, v3, v22
	s_waitcnt lgkmcnt(4)
	v_cvt_pk_bf16_f32 v23, v23, v24
	s_waitcnt lgkmcnt(2)
	v_cvt_pk_bf16_f32 v24, v25, v28
	s_waitcnt lgkmcnt(0)
	v_cvt_pk_bf16_f32 v25, v29, v30
	global_store_dwordx4 v[26:27], v[22:25], off offset:16
	ds_read_b32 v3, v21 offset:16640
	ds_read_b32 v22, v21 offset:17680
	ds_read_b32 v23, v21 offset:18720
	ds_read_b32 v24, v21 offset:19760
	ds_read_b32 v25, v21 offset:20800
	ds_read_b32 v28, v21 offset:21840
	ds_read_b32 v29, v21 offset:22880
	ds_read_b32 v30, v21 offset:23920
	s_waitcnt lgkmcnt(6)
	v_cvt_pk_bf16_f32 v22, v3, v22
	s_waitcnt lgkmcnt(4)
	v_cvt_pk_bf16_f32 v23, v23, v24
	s_waitcnt lgkmcnt(2)
	v_cvt_pk_bf16_f32 v24, v25, v28
	s_waitcnt lgkmcnt(0)
	v_cvt_pk_bf16_f32 v25, v29, v30
	global_store_dwordx4 v[26:27], v[22:25], off offset:32
	ds_read_b32 v3, v21 offset:24960
	ds_read_b32 v22, v21 offset:26000
	ds_read_b32 v23, v21 offset:27040
	ds_read_b32 v24, v21 offset:28080
	ds_read_b32 v25, v21 offset:29120
	ds_read_b32 v28, v21 offset:30160
	ds_read_b32 v29, v21 offset:31200
	ds_read_b32 v30, v21 offset:32240
	s_waitcnt lgkmcnt(6)
	v_cvt_pk_bf16_f32 v22, v3, v22
	s_waitcnt lgkmcnt(4)
	v_cvt_pk_bf16_f32 v23, v23, v24
	s_waitcnt lgkmcnt(2)
	v_cvt_pk_bf16_f32 v24, v25, v28
	s_waitcnt lgkmcnt(0)
	v_cvt_pk_bf16_f32 v25, v29, v30
	global_store_dwordx4 v[26:27], v[22:25], off offset:48
	s_barrier
	s_cbranch_scc1 .LBB0_280
; __device__ __forceinline__ int otid(int wv) { int t; asm volatile("v_mbcnt_lo_u32_b32 %0, -1, 0\n\tv_mbcnt_hi_u32_b32 %0, -1, %0\n\tv_lshl_add_u32 %0, %1, 6, %0" : "=&v"(t) : "s"(wv)); return t; }
; __device__ __forceinline__ unsigned cvt_pk_bf16(float lo, float hi) { const f2_t v = {lo, hi}; const bf2_t b = __builtin_convertvector(v, bf2_t); return __builtin_bit_cast(unsigned, b); }
; __device__ __forceinline__ int upcol(int n) { return (n >> 8) * 128 + (n & 127) + ((n & 128) ? FFD : 0); }
; __device__ void convert_matrix(int wv, const float* src, int K, int N, int ld, int perm, bf16_t* dst, float* tileL, int rot) {
;     const int tid = otid(wv), G = gridDim.x, ntk = K >> 6, ntiles = ntk * (N >> 8);
;     for (int t = (blockIdx.x + G - (rot % G)) % G; t < ntiles; t += G) {
;         const int k0 = (t % ntk) * 64, n0 = (t / ntk) * 256;
;         f32x4 v[8];
; #pragma unroll
;         for (int ps = 0; ps < 8; ++ps) { const int idx = tid + ps * NTHR, kk = idx >> 6, n4 = (idx & 63) * 4; const int sc = perm ? upcol(n0 + n4) : n0 + n4;
;             v[ps] = *(const f32x4*)(src + (size_t)(k0 + kk) * ld + sc); }
; #pragma unroll
;         for (int ps = 0; ps < 8; ++ps) { const int idx = tid + ps * NTHR, kk = idx >> 6, n4 = (idx & 63) * 4;
;             float* tp = tileL + kk * 257 + n4; tp[0] = v[ps][0]; tp[1] = v[ps][1]; tp[2] = v[ps][2]; tp[3] = v[ps][3]; }
;         __syncthreads();
;         { const int n = tid >> 1, kh = (tid & 1) * 32;
; #pragma unroll
;             for (int q = 0; q < 4; ++q) { float e[8];
; #pragma unroll
;                 for (int j = 0; j < 8; ++j) e[j] = tileL[(kh + 8 * q + j) * 257 + n];
;                 u32x4 w; w.x = cvt_pk_bf16(e[0], e[1]); w.y = cvt_pk_bf16(e[2], e[3]); w.z = cvt_pk_bf16(e[4], e[5]); w.w = cvt_pk_bf16(e[6], e[7]);
;                 *(u32x4*)(dst + (size_t)(n0 + n) * K + k0 + kh + 8 * q) = w; } }
;         __syncthreads();
; __global__ void __launch_bounds__(NTHR, 2) mega(Params p) {
;     ...
;             convert_matrix(wv, p.f_w_down + (size_t)(i + 1) * FFD * 1024, FFD, 1024, 1024, 0, wdn + (size_t)((i + 1) & 1) * 1024 * FFD, ldsf, 96);
.LBB0_281:
	v_readlane_b32 s4, v254, 7
	v_readlane_b32 s5, v254, 8
	s_andn2_b64 vcc, exec, s[4:5]
	v_mbcnt_lo_u32_b32 v2, -1, 0
	v_mbcnt_hi_u32_b32 v2, -1, v2
	v_lshl_add_u32 v2, s33, 6, v2
	s_cbranch_vccnz .LBB0_284
	v_add_u32_e32 v7, 0x200, v2
	v_ashrrev_i32_e32 v24, 6, v7
	v_add_u32_e32 v7, 0x400, v2
	v_ashrrev_i32_e32 v25, 6, v7
	v_add_u32_e32 v7, 0x600, v2
	v_ashrrev_i32_e32 v26, 6, v7
	v_add_u32_e32 v7, 0x800, v2
	s_mul_hi_u32 s5, s15, 0xb00000
	s_mul_i32 s15, s15, 0xb00000
	v_ashrrev_i32_e32 v27, 6, v7
	v_add_u32_e32 v7, 0xa00, v2
	s_add_u32 s4, s24, s15
	v_lshlrev_b32_e32 v1, 2, v2
	v_ashrrev_i32_e32 v22, 1, v2
	v_lshlrev_b32_e32 v4, 5, v2
	v_ashrrev_i32_e32 v23, 6, v2
	v_ashrrev_i32_e32 v28, 6, v7
	v_add_u32_e32 v7, 0xc00, v2
	v_add_u32_e32 v2, 0xe00, v2
	s_addc_u32 s5, s25, s5
	s_mul_i32 s14, s14, 0x580000
	v_and_b32_e32 v1, 0xfc, v1
	v_and_b32_e32 v4, 32, v4
	v_ashrrev_i32_e32 v29, 6, v7
	v_ashrrev_i32_e32 v30, 6, v2
	s_movk_i32 s10, 0x404
	s_add_u32 s6, s41, s14
	v_lshl_add_u32 v3, v1, 2, 0
	v_lshl_add_u32 v5, v22, 2, 0
	v_mul_u32_u24_e32 v6, 0x412, v4
	v_mul_lo_u32 v2, v23, s10
	v_mul_lo_u32 v7, v24, s10
	v_mul_lo_u32 v8, v25, s10
	v_mul_lo_u32 v9, v26, s10
	v_mul_lo_u32 v10, v27, s10
	v_mul_lo_u32 v11, v28, s10
	v_mul_lo_u32 v12, v29, s10
	v_mul_lo_u32 v13, v30, s10
	v_readlane_b32 s16, v253, 34
	s_addc_u32 s7, s64, 0
	s_lshl_b32 s14, s16, 6
	s_lshl_b32 s15, s34, 6
	v_add_u32_e32 v31, v3, v2
	v_mad_u32_u24 v31, v23, 12, v31
	v_add_u32_e32 v32, v3, v7
	v_add_u32_e32 v33, v3, v8
	v_add_u32_e32 v34, v3, v9
	v_add_u32_e32 v35, v3, v10
	v_add_u32_e32 v36, v3, v11
	v_add_u32_e32 v37, v3, v12
	v_add_u32_e32 v38, v3, v13
	v_lshlrev_b32_e32 v18, 1, v4
	v_add_u32_e32 v39, v5, v6
.LBB0_283:
	s_mul_hi_i32 s10, s16, 0x2e8ba2e9
	s_lshr_b32 s11, s10, 31
	s_ashr_i32 s10, s10, 3
	s_add_i32 s11, s10, s11
	s_mul_i32 s10, s11, 0xfffff500
	s_add_i32 s10, s14, s10
	s_lshl_b32 s11, s11, 8
	v_add_u32_e32 v4, s10, v23
	v_or_b32_e32 v2, s11, v1
	v_ashrrev_i32_e32 v5, 31, v4
	v_lshlrev_b64 v[4:5], 12, v[4:5]
	v_ashrrev_i32_e32 v3, 31, v2
	v_add_u32_e32 v6, s10, v24
	v_lshl_add_u64 v[4:5], s[4:5], 0, v[4:5]
	v_lshlrev_b64 v[20:21], 2, v[2:3]
	v_ashrrev_i32_e32 v7, 31, v6
	v_lshl_add_u64 v[2:3], v[4:5], 0, v[20:21]
	v_lshlrev_b64 v[6:7], 12, v[6:7]
	v_add_u32_e32 v10, s10, v25
	global_load_dwordx4 v[2:5], v[2:3], off
	v_lshl_add_u64 v[6:7], s[4:5], 0, v[6:7]
	v_ashrrev_i32_e32 v11, 31, v10
	v_lshl_add_u64 v[6:7], v[6:7], 0, v[20:21]
	v_lshlrev_b64 v[10:11], 12, v[10:11]
	v_add_u32_e32 v14, s10, v26
	global_load_dwordx4 v[6:9], v[6:7], off
	v_lshl_add_u64 v[10:11], s[4:5], 0, v[10:11]
	v_ashrrev_i32_e32 v15, 31, v14
	v_lshl_add_u64 v[10:11], v[10:11], 0, v[20:21]
	v_lshlrev_b64 v[14:15], 12, v[14:15]
	v_add_u32_e32 v40, s10, v27
	global_load_dwordx4 v[10:13], v[10:11], off
	v_lshl_add_u64 v[14:15], s[4:5], 0, v[14:15]
	v_ashrrev_i32_e32 v41, 31, v40
	v_lshl_add_u64 v[14:15], v[14:15], 0, v[20:21]
	v_lshlrev_b64 v[40:41], 12, v[40:41]
	v_add_u32_e32 v44, s10, v28
	global_load_dwordx4 v[14:17], v[14:15], off
	v_lshl_add_u64 v[40:41], s[4:5], 0, v[40:41]
	v_ashrrev_i32_e32 v45, 31, v44
	v_lshl_add_u64 v[40:41], v[40:41], 0, v[20:21]
	v_lshlrev_b64 v[44:45], 12, v[44:45]
	v_add_u32_e32 v48, s10, v29
	global_load_dwordx4 v[40:43], v[40:41], off
	v_lshl_add_u64 v[44:45], s[4:5], 0, v[44:45]
	v_ashrrev_i32_e32 v49, 31, v48
	v_lshl_add_u64 v[44:45], v[44:45], 0, v[20:21]
	v_lshlrev_b64 v[48:49], 12, v[48:49]
	v_add_u32_e32 v52, s10, v30
	global_load_dwordx4 v[44:47], v[44:45], off
	v_lshl_add_u64 v[48:49], s[4:5], 0, v[48:49]
	v_ashrrev_i32_e32 v53, 31, v52
	v_lshl_add_u64 v[48:49], v[48:49], 0, v[20:21]
	v_lshlrev_b64 v[52:53], 12, v[52:53]
	global_load_dwordx4 v[48:51], v[48:49], off
	v_lshl_add_u64 v[52:53], s[4:5], 0, v[52:53]
	v_lshl_add_u64 v[20:21], v[52:53], 0, v[20:21]
	global_load_dwordx4 v[52:55], v[20:21], off
	v_mov_b32_e32 v19, v0
	s_add_i32 s16, s16, s34
	s_add_i32 s14, s14, s15
	s_waitcnt vmcnt(7)
	ds_write_b128 v31, v[2:5]
	s_waitcnt vmcnt(6)
	ds_write_b128 v31, v[6:9] offset:8320
	s_waitcnt vmcnt(5)
	ds_write_b128 v31, v[10:13] offset:16640
	s_waitcnt vmcnt(4)
	ds_write_b128 v31, v[14:17] offset:24960
	s_waitcnt vmcnt(3)
	ds_write_b128 v31, v[40:43] offset:33344
	s_waitcnt vmcnt(2)
	ds_write_b128 v31, v[44:47] offset:41664
	s_waitcnt vmcnt(1)
	ds_write_b128 v31, v[48:51] offset:49984
	s_waitcnt vmcnt(0)
	ds_write_b128 v31, v[52:55] offset:58304
	v_add_u32_e32 v4, s11, v22
	v_mov_b64_e32 v[2:3], s[6:7]
	v_mad_i64_i32 v[2:3], s[20:21], v4, s45, v[2:3]
	s_ashr_i32 s11, s10, 31
	v_lshl_add_u64 v[2:3], s[10:11], 1, v[2:3]
	s_waitcnt lgkmcnt(0)
	s_barrier
	v_lshl_add_u64 v[6:7], v[2:3], 0, v[18:19]
	ds_read_b32 v2, v39
	ds_read_b32 v3, v39 offset:1040
	ds_read_b32 v4, v39 offset:2080
	ds_read_b32 v5, v39 offset:3120
	ds_read_b32 v8, v39 offset:4160
	ds_read_b32 v9, v39 offset:5200
	ds_read_b32 v10, v39 offset:6240
	ds_read_b32 v11, v39 offset:7280
	s_waitcnt lgkmcnt(6)
	v_cvt_pk_bf16_f32 v2, v2, v3
	s_waitcnt lgkmcnt(4)
	v_cvt_pk_bf16_f32 v3, v4, v5
	s_waitcnt lgkmcnt(2)
	v_cvt_pk_bf16_f32 v4, v8, v9
	s_cmpk_lt_i32 s16, 0xb0
	s_waitcnt lgkmcnt(0)
	v_cvt_pk_bf16_f32 v5, v10, v11
	global_store_dwordx4 v[6:7], v[2:5], off
	ds_read_b32 v2, v39 offset:8320
	ds_read_b32 v3, v39 offset:9360
	ds_read_b32 v4, v39 offset:10400
	ds_read_b32 v5, v39 offset:11440
	ds_read_b32 v8, v39 offset:12480
	ds_read_b32 v9, v39 offset:13520
	ds_read_b32 v10, v39 offset:14560
	ds_read_b32 v11, v39 offset:15600
	s_waitcnt lgkmcnt(6)
	v_cvt_pk_bf16_f32 v2, v2, v3
	s_waitcnt lgkmcnt(4)
	v_cvt_pk_bf16_f32 v3, v4, v5
	s_waitcnt lgkmcnt(2)
	v_cvt_pk_bf16_f32 v4, v8, v9
	s_waitcnt lgkmcnt(0)
	v_cvt_pk_bf16_f32 v5, v10, v11
	global_store_dwordx4 v[6:7], v[2:5], off offset:16
	ds_read_b32 v2, v39 offset:16640
	ds_read_b32 v3, v39 offset:17680
	ds_read_b32 v4, v39 offset:18720
	ds_read_b32 v5, v39 offset:19760
	ds_read_b32 v8, v39 offset:20800
	ds_read_b32 v9, v39 offset:21840
	ds_read_b32 v10, v39 offset:22880
	ds_read_b32 v11, v39 offset:23920
	s_waitcnt lgkmcnt(6)
	v_cvt_pk_bf16_f32 v2, v2, v3
	s_waitcnt lgkmcnt(4)
	v_cvt_pk_bf16_f32 v3, v4, v5
	s_waitcnt lgkmcnt(2)
	v_cvt_pk_bf16_f32 v4, v8, v9
	s_waitcnt lgkmcnt(0)
	v_cvt_pk_bf16_f32 v5, v10, v11
	global_store_dwordx4 v[6:7], v[2:5], off offset:32
	ds_read_b32 v2, v39 offset:24960
	ds_read_b32 v3, v39 offset:26000
	ds_read_b32 v4, v39 offset:27040
	ds_read_b32 v5, v39 offset:28080
	ds_read_b32 v8, v39 offset:29120
	ds_read_b32 v9, v39 offset:30160
	ds_read_b32 v10, v39 offset:31200
	ds_read_b32 v11, v39 offset:32240
	s_waitcnt lgkmcnt(6)
	v_cvt_pk_bf16_f32 v2, v2, v3
	s_waitcnt lgkmcnt(4)
	v_cvt_pk_bf16_f32 v3, v4, v5
	s_waitcnt lgkmcnt(2)
	v_cvt_pk_bf16_f32 v4, v8, v9
	s_waitcnt lgkmcnt(0)
	v_cvt_pk_bf16_f32 v5, v10, v11
	global_store_dwordx4 v[6:7], v[2:5], off offset:48
	s_barrier
	s_cbranch_scc1 .LBB0_283
